# FoX unit body fully hand-scheduled too: steady loop plus causal diagonal tail (full / masked-QK / last-tile / idle variants per wave)
# speedup vs baseline: 1.0275x; 1.0136x over previous
.LBB0_654:
	v_lshlrev_b32_e32 v16, 3, v18
	v_lshrrev_b32_e32 v14, 2, v19
	v_lshlrev_b32_e32 v15, 1, v18
	v_and_b32_e32 v16, 24, v16
	v_and_or_b32 v15, v15, 32, v16
	v_and_or_b32 v14, v14, 3, v156
	v_lshl_or_b32 v14, v14, 6, v15
	v_lshl_add_u64 v[136:137], v[12:13], 1, s[12:13]
	s_add_i32 s12, s10, 2
	v_mul_u32_u24_e32 v164, 0x90, v20
	v_lshl_add_u64 v[138:139], v[144:145], 1, s[14:15]
	s_cmp_ge_i32 s12, s35
	v_add_u32_e32 v158, 0, v30
	v_add_u32_e32 v159, 0, v14
	s_barrier
	v_add_u32_e32 v218, v164, v30
	s_and_b32 s12, s33, 1
	s_lshl_b32 s12, s12, 5
	v_lshlrev_b32_e32 v219, 2, v21
	v_sub_u32_e32 v219, v20, v219
	v_add_u32_e32 v219, s12, v219
	s_lshr_b32 s11, s33, 1
	v_mov_b32_e32 v14, 0
	v_mov_b32_e32 v15, 0
	v_mov_b32_e32 v16, 0
	v_mov_b32_e32 v17, 0
	v_mov_b32_e32 v18, 0
	v_mov_b32_e32 v19, 0
	v_mov_b32_e32 v20, 0
	v_mov_b32_e32 v21, 0
	v_mov_b32_e32 v22, 0
	v_mov_b32_e32 v23, 0
	v_mov_b32_e32 v24, 0
	v_mov_b32_e32 v25, 0
	v_mov_b32_e32 v26, 0
	v_mov_b32_e32 v27, 0
	v_mov_b32_e32 v28, 0
	v_mov_b32_e32 v29, 0
	v_mov_b32_e32 v30, 0
	v_mov_b32_e32 v31, 0
	v_mov_b32_e32 v32, 0
	v_mov_b32_e32 v33, 0
	v_mov_b32_e32 v34, 0
	v_mov_b32_e32 v35, 0
	v_mov_b32_e32 v36, 0
	v_mov_b32_e32 v37, 0
	v_mov_b32_e32 v38, 0
	v_mov_b32_e32 v39, 0
	v_mov_b32_e32 v40, 0
	v_mov_b32_e32 v41, 0
	v_mov_b32_e32 v42, 0
	v_mov_b32_e32 v43, 0
	v_mov_b32_e32 v44, 0
	v_mov_b32_e32 v45, 0
	v_mov_b32_e32 v161, 0
	v_mov_b32_e32 v160, 0xf149f2ca
	s_add_i32 s12, s10, 2
	s_ashr_i32 s13, s12, 31
	s_lshl_b64 s[14:15], s[12:13], 16
	v_lshl_add_u64 v[244:245], v[136:137], 0, s[14:15]
	s_lshl_b64 s[14:15], s[12:13], 8
	v_mov_b32_e32 v141, 0
	v_lshl_add_u64 v[250:251], s[4:5], 0, v[140:141]
	v_lshl_add_u64 v[250:251], v[250:251], 0, s[14:15]
	s_add_i32 s12, s10, 1
	s_ashr_i32 s13, s12, 31
	s_lshl_b64 s[14:15], s[12:13], 16
	v_lshl_add_u64 v[248:249], v[138:139], 0, s[14:15]
	global_load_dwordx4 v[114:117], v[244:245], off
	s_and_saveexec_b64 s[12:13], s[6:7]
	s_cbranch_execz .Lf3_nockp
	global_load_dword v152, v[250:251], off
.Lf3_nockp:
	s_or_b64 exec, exec, s[12:13]
	global_load_dwordx4 v[118:121], v[248:249], off
	s_mov_b64 s[14:15], 0x10000
	v_lshl_add_u64 v[242:243], v[244:245], 0, s[14:15]
	v_lshl_add_u64 v[244:245], v[242:243], 0, s[14:15]
	v_lshl_add_u64 v[246:247], v[248:249], 0, s[14:15]
	v_lshl_add_u64 v[248:249], v[246:247], 0, s[14:15]
	s_mov_b64 s[14:15], 0x100
	v_lshl_add_u64 v[250:251], v[250:251], 0, s[14:15]
	ds_read_b128 v[78:81], v158 offset:43264
	ds_read_b128 v[82:85], v158 offset:43296
	ds_read_b128 v[86:89], v158 offset:43328
	ds_read_b128 v[90:93], v158 offset:43360
	ds_read_b128 v[94:97], v158 offset:43392
	ds_read_b128 v[98:101], v158 offset:43424
	ds_read_b128 v[102:105], v158 offset:43456
	ds_read_b128 v[106:109], v158 offset:43488
	s_waitcnt lgkmcnt(4)
	ds_read_b128 v[190:193], v218 offset:13312
	ds_read_b128 v[194:197], v218 offset:17920
	ds_read_b128 v[198:201], v218 offset:13344
	ds_read_b128 v[202:205], v218 offset:17952
	ds_read_b128 v[206:209], v218 offset:13376
	ds_read_b128 v[210:213], v218 offset:17984
	ds_read_b128 v[214:217], v218 offset:13408
	ds_read_b128 v[222:225], v218 offset:18016
	v_max3_f32 v124, v46, v47, v48
	v_max3_f32 v125, v49, v50, v51
	v_max3_f32 v124, v124, v52, v53
	v_max3_f32 v125, v125, v54, v55
	v_max3_f32 v124, v124, v56, v57
	v_max3_f32 v125, v125, v58, v59
	v_max3_f32 v124, v124, v60, v61
	v_max3_f32 v125, v125, v62, v63
	v_max3_f32 v124, v124, v64, v65
	v_max3_f32 v125, v125, v66, v67
	v_max3_f32 v124, v124, v68, v69
	v_max3_f32 v125, v125, v70, v71
	v_max3_f32 v124, v124, v72, v73
	v_max3_f32 v125, v125, v74, v75
	v_max3_f32 v124, v124, v76, v77
	v_max_f32_e32 v124, v124, v125
	v_mov_b32_e32 v125, v124
	s_nop 1
	v_permlane32_swap_b32_e32 v124, v125
	v_max_f32_e32 v126, v124, v125
	s_add_i32 s12, s10, 6
	s_cmp_lt_i32 s12, s41
	s_cbranch_scc1 .Lf3_loop
	s_add_i32 s12, s10, 4
	s_cmp_lt_i32 s12, s41
	s_cbranch_scc1 .Lf3_tail0
	s_branch .Lf3_tail2

.Lf3_nockb:
	s_or_b64 exec, exec, s[12:13]
	global_load_dwordx4 v[118:121], v[248:249], off
	v_max3_f32 v125, v125, v54, v55
	v_max3_f32 v124, v124, v56, v57
	v_max3_f32 v125, v125, v58, v59
	v_mfma_f32_32x32x16_bf16 v[14:29], v[198:201], v[230:233], v[14:29]
	ds_read_b128 v[198:201], v218 offset:13344
	v_max3_f32 v124, v124, v60, v61
	v_max3_f32 v125, v125, v62, v63
	v_max3_f32 v124, v124, v64, v65
	v_mfma_f32_32x32x16_bf16 v[30:45], v[202:205], v[230:233], v[30:45]
	ds_read_b128 v[202:205], v218 offset:17952
	v_max3_f32 v125, v125, v66, v67
	v_max3_f32 v124, v124, v68, v69
	v_max3_f32 v125, v125, v70, v71
	v_mfma_f32_32x32x16_bf16 v[14:29], v[206:209], v[234:237], v[14:29]
	ds_read_b128 v[206:209], v218 offset:13376
	v_max3_f32 v124, v124, v72, v73
	v_max3_f32 v125, v125, v74, v75
	v_mfma_f32_32x32x16_bf16 v[30:45], v[210:213], v[234:237], v[30:45]
	ds_read_b128 v[210:213], v218 offset:17984
	v_max3_f32 v124, v124, v76, v77
	v_max_f32_e32 v124, v124, v125
	v_mfma_f32_32x32x16_bf16 v[14:29], v[214:217], v[238:241], v[14:29]
	ds_read_b128 v[214:217], v218 offset:13408
	v_mov_b32_e32 v125, v124
	s_nop 1
	v_mfma_f32_32x32x16_bf16 v[30:45], v[222:225], v[238:241], v[30:45]
	s_waitcnt lgkmcnt(14)
	ds_read_b128 v[222:225], v218 offset:18016
	v_permlane32_swap_b32_e32 v124, v125
	v_max_f32_e32 v126, v124, v125
	v_lshl_add_u64 v[244:245], v[244:245], 0, s[46:47]
	v_lshl_add_u64 v[248:249], v[248:249], 0, s[46:47]
	v_lshl_add_u64 v[250:251], v[250:251], 0, s[48:49]
	s_add_i32 s10, s10, 2
	s_add_i32 s12, s10, 6
	s_cmp_lt_i32 s12, s41
	s_cbranch_scc1 .Lf3_loop

.Lf3_tail1:
	s_cmp_ge_u32 s11, 1
	s_cbranch_scc1 .Lf3_t1_FULL
	v_add_f32_e32 v127, 0x41800000, v160
	v_cmp_gt_f32_e32 vcc, v126, v127
	s_cbranch_vccnz .Lf3_resct1FULLM

.Lf3_nocwt1FULLM:
	s_or_b64 exec, exec, s[12:13]
	ds_write_b128 v155, v[118:121] offset:26624
	v_exp_f32_e32 v102, v102
	v_exp_f32_e32 v103, v103
	v_exp_f32_e32 v104, v104
	v_exp_f32_e32 v105, v105
	v_exp_f32_e32 v106, v106
	v_exp_f32_e32 v107, v107
	v_exp_f32_e32 v108, v108
	v_exp_f32_e32 v109, v109
	v_add_f32_e32 v122, v122, v102
	v_add_f32_e32 v123, v123, v103
	v_add_f32_e32 v122, v122, v104
	v_add_f32_e32 v123, v123, v105
	v_add_f32_e32 v122, v122, v106
	v_add_f32_e32 v123, v123, v107
	v_add_f32_e32 v122, v122, v108
	v_add_f32_e32 v123, v123, v109
	v_cvt_pk_bf16_f32 v238, v102, v103
	v_cvt_pk_bf16_f32 v239, v104, v105
	v_cvt_pk_bf16_f32 v240, v106, v107
	v_cvt_pk_bf16_f32 v241, v108, v109
	v_add_f32_e32 v122, v122, v123
	v_add_f32_e32 v161, v161, v122
	s_waitcnt lgkmcnt(0)
	s_barrier
	ds_read_b128 v[78:81], v158 offset:43264
	ds_read_b128 v[82:85], v158 offset:43296
	ds_read_b128 v[86:89], v158 offset:43328
	ds_read_b128 v[90:93], v158 offset:43360
	ds_read_b128 v[94:97], v158 offset:43392
	ds_read_b128 v[98:101], v158 offset:43424
	ds_read_b128 v[102:105], v158 offset:43456
	ds_read_b128 v[106:109], v158 offset:43488
	v_mfma_f32_32x32x16_bf16 v[14:29], v[190:193], v[226:229], v[14:29]
	ds_read_b128 v[190:193], v218 offset:13312
	v_cmp_le_i32_e64 s[52:53], 0, v219
	v_cmp_le_i32_e64 s[14:15], 32, v219
	v_cmp_le_i32_e64 s[16:17], 1, v219
	v_cndmask_b32_e64 v46, v220, v46, s[52:53]
	v_cmp_le_i32_e64 s[52:53], 33, v219
	v_cndmask_b32_e64 v62, v220, v62, s[14:15]
	v_cmp_le_i32_e64 s[14:15], 2, v219
	v_cndmask_b32_e64 v47, v220, v47, s[16:17]
	v_cmp_le_i32_e64 s[16:17], 34, v219
	v_cndmask_b32_e64 v63, v220, v63, s[52:53]
	v_cmp_le_i32_e64 s[52:53], 3, v219
	v_mfma_f32_32x32x16_bf16 v[30:45], v[194:197], v[226:229], v[30:45]
	ds_read_b128 v[194:197], v218 offset:17920
	global_load_dwordx4 v[114:117], v[244:245], off
	s_and_saveexec_b64 s[12:13], s[6:7]
	s_cbranch_execz .Lf3_nockt1FULLM
	global_load_dword v152, v[250:251], off offset:256
.Lf3_nockt1FULLM:
	s_or_b64 exec, exec, s[12:13]
	global_load_dwordx4 v[118:121], v[248:249], off
	v_cndmask_b32_e64 v48, v220, v48, s[14:15]
	v_cmp_le_i32_e64 s[14:15], 35, v219
	v_cndmask_b32_e64 v64, v220, v64, s[16:17]
	v_cmp_le_i32_e64 s[16:17], 8, v219
	v_cndmask_b32_e64 v49, v220, v49, s[52:53]
	v_cmp_le_i32_e64 s[52:53], 40, v219
	v_cndmask_b32_e64 v65, v220, v65, s[14:15]
	v_cmp_le_i32_e64 s[14:15], 9, v219
	v_cndmask_b32_e64 v50, v220, v50, s[16:17]
	v_cmp_le_i32_e64 s[16:17], 41, v219
	v_cndmask_b32_e64 v66, v220, v66, s[52:53]
	v_mfma_f32_32x32x16_bf16 v[14:29], v[198:201], v[230:233], v[14:29]
	ds_read_b128 v[198:201], v218 offset:13344
	v_cmp_le_i32_e64 s[52:53], 10, v219
	v_cndmask_b32_e64 v51, v220, v51, s[14:15]
	v_cmp_le_i32_e64 s[14:15], 42, v219
	v_cndmask_b32_e64 v67, v220, v67, s[16:17]
	v_cmp_le_i32_e64 s[16:17], 11, v219
	v_cndmask_b32_e64 v52, v220, v52, s[52:53]
	v_cmp_le_i32_e64 s[52:53], 43, v219
	v_cndmask_b32_e64 v68, v220, v68, s[14:15]
	v_cmp_le_i32_e64 s[14:15], 16, v219
	v_cndmask_b32_e64 v53, v220, v53, s[16:17]
	v_cmp_le_i32_e64 s[16:17], 48, v219
	v_mfma_f32_32x32x16_bf16 v[30:45], v[202:205], v[230:233], v[30:45]
	ds_read_b128 v[202:205], v218 offset:17952
	v_cndmask_b32_e64 v69, v220, v69, s[52:53]
	v_cmp_le_i32_e64 s[52:53], 17, v219
	v_cndmask_b32_e64 v54, v220, v54, s[14:15]
	v_cmp_le_i32_e64 s[14:15], 49, v219
	v_cndmask_b32_e64 v70, v220, v70, s[16:17]
	v_cmp_le_i32_e64 s[16:17], 18, v219
	v_cndmask_b32_e64 v55, v220, v55, s[52:53]
	v_cmp_le_i32_e64 s[52:53], 50, v219
	v_cndmask_b32_e64 v71, v220, v71, s[14:15]
	v_cmp_le_i32_e64 s[14:15], 19, v219
	v_cndmask_b32_e64 v56, v220, v56, s[16:17]
	v_mfma_f32_32x32x16_bf16 v[14:29], v[206:209], v[234:237], v[14:29]
	ds_read_b128 v[206:209], v218 offset:13376
	v_cmp_le_i32_e64 s[16:17], 51, v219
	v_cndmask_b32_e64 v72, v220, v72, s[52:53]
	v_cmp_le_i32_e64 s[52:53], 24, v219
	v_cndmask_b32_e64 v57, v220, v57, s[14:15]
	v_cmp_le_i32_e64 s[14:15], 56, v219
	v_cndmask_b32_e64 v73, v220, v73, s[16:17]
	v_cmp_le_i32_e64 s[16:17], 25, v219
	v_cndmask_b32_e64 v58, v220, v58, s[52:53]
	v_cmp_le_i32_e64 s[52:53], 57, v219
	v_cndmask_b32_e64 v74, v220, v74, s[14:15]
	v_mfma_f32_32x32x16_bf16 v[30:45], v[210:213], v[234:237], v[30:45]
	ds_read_b128 v[210:213], v218 offset:17984
	v_cmp_le_i32_e64 s[14:15], 26, v219
	v_cndmask_b32_e64 v59, v220, v59, s[16:17]
	v_cmp_le_i32_e64 s[16:17], 58, v219
	v_cndmask_b32_e64 v75, v220, v75, s[52:53]
	v_cmp_le_i32_e64 s[52:53], 27, v219
	v_cndmask_b32_e64 v60, v220, v60, s[14:15]
	v_cmp_le_i32_e64 s[14:15], 59, v219
	v_cndmask_b32_e64 v76, v220, v76, s[16:17]
	v_cndmask_b32_e64 v61, v220, v61, s[52:53]
	v_cndmask_b32_e64 v77, v220, v77, s[14:15]
	v_mfma_f32_32x32x16_bf16 v[14:29], v[214:217], v[238:241], v[14:29]
	ds_read_b128 v[214:217], v218 offset:13408
	v_max3_f32 v124, v46, v47, v48
	v_max3_f32 v125, v49, v50, v51
	v_max3_f32 v124, v124, v52, v53
	v_max3_f32 v125, v125, v54, v55
	v_max3_f32 v124, v124, v56, v57
	v_max3_f32 v125, v125, v58, v59
	v_max3_f32 v124, v124, v60, v61
	v_max3_f32 v125, v125, v62, v63
	v_max3_f32 v124, v124, v64, v65
	v_max3_f32 v125, v125, v66, v67
	v_mfma_f32_32x32x16_bf16 v[30:45], v[222:225], v[238:241], v[30:45]
	s_waitcnt lgkmcnt(14)
	ds_read_b128 v[222:225], v218 offset:18016
	v_max3_f32 v124, v124, v68, v69
	v_max3_f32 v125, v125, v70, v71
	v_max3_f32 v124, v124, v72, v73
	v_max3_f32 v125, v125, v74, v75
	v_max3_f32 v124, v124, v76, v77
	v_max_f32_e32 v124, v124, v125
	v_mov_b32_e32 v125, v124
	s_nop 1
	v_permlane32_swap_b32_e32 v124, v125
	v_max_f32_e32 v126, v124, v125
	v_lshl_add_u64 v[244:245], v[244:245], 0, s[46:47]
	v_lshl_add_u64 v[248:249], v[248:249], 0, s[46:47]
	v_lshl_add_u64 v[250:251], v[250:251], 0, s[48:49]
	s_branch .Lf3_tail2
.Lf3_t1_FULL:
	v_add_f32_e32 v127, 0x41800000, v160
	v_cmp_gt_f32_e32 vcc, v126, v127
	s_cbranch_vccnz .Lf3_resct1FULL
.Lf3_resc_rett1FULL:
	s_waitcnt lgkmcnt(7)
	v_mfma_f32_32x32x16_bf16 v[46:61], v[190:193], v[0:3], v[46:61]
	ds_read_b64_tr_b16 v[190:191], v159 offset:34816
	ds_read_b64_tr_b16 v[192:193], v159 offset:35328
	v_sub_f32_e32 v78, v78, v160
	v_sub_f32_e32 v79, v79, v160
	v_sub_f32_e32 v80, v80, v160
	v_sub_f32_e32 v81, v81, v160
	v_sub_f32_e32 v82, v82, v160
	v_sub_f32_e32 v83, v83, v160
	v_sub_f32_e32 v84, v84, v160
	v_sub_f32_e32 v85, v85, v160
	v_exp_f32_e32 v78, v78
	v_exp_f32_e32 v79, v79
	v_exp_f32_e32 v80, v80
	v_exp_f32_e32 v81, v81
	s_waitcnt lgkmcnt(8)
	v_mfma_f32_32x32x16_bf16 v[62:77], v[194:197], v[0:3], v[62:77]
	ds_read_b64_tr_b16 v[194:195], v159 offset:38912
	ds_read_b64_tr_b16 v[196:197], v159 offset:39424
	v_exp_f32_e32 v82, v82
	v_exp_f32_e32 v83, v83
	v_exp_f32_e32 v84, v84
	v_exp_f32_e32 v85, v85
	v_add_f32_e32 v122, v78, v79
	v_add_f32_e32 v123, v80, v81
	v_add_f32_e32 v122, v122, v82
	v_add_f32_e32 v123, v123, v83
	v_add_f32_e32 v122, v122, v84
	v_add_f32_e32 v123, v123, v85
	v_cvt_pk_bf16_f32 v226, v78, v79
	v_cvt_pk_bf16_f32 v227, v80, v81
	s_waitcnt lgkmcnt(9)
	v_mfma_f32_32x32x16_bf16 v[46:61], v[198:201], v[4:7], v[46:61]
	ds_read_b64_tr_b16 v[198:199], v159 offset:35840
	ds_read_b64_tr_b16 v[200:201], v159 offset:36352
	v_cvt_pk_bf16_f32 v228, v82, v83
	v_cvt_pk_bf16_f32 v229, v84, v85
	v_sub_f32_e32 v86, v86, v160
	v_sub_f32_e32 v87, v87, v160
	v_sub_f32_e32 v88, v88, v160
	v_sub_f32_e32 v89, v89, v160
	v_sub_f32_e32 v90, v90, v160
	v_sub_f32_e32 v91, v91, v160
	v_sub_f32_e32 v92, v92, v160
	v_sub_f32_e32 v93, v93, v160
	v_exp_f32_e32 v86, v86
	s_waitcnt lgkmcnt(10)
	v_mfma_f32_32x32x16_bf16 v[62:77], v[202:205], v[4:7], v[62:77]
	ds_read_b64_tr_b16 v[202:203], v159 offset:39936
	ds_read_b64_tr_b16 v[204:205], v159 offset:40448
	v_exp_f32_e32 v87, v87
	v_exp_f32_e32 v88, v88
	v_exp_f32_e32 v89, v89
	v_exp_f32_e32 v90, v90
	v_exp_f32_e32 v91, v91
	v_exp_f32_e32 v92, v92
	v_exp_f32_e32 v93, v93
	v_add_f32_e32 v122, v122, v86
	v_add_f32_e32 v123, v123, v87
	v_add_f32_e32 v122, v122, v88
	v_add_f32_e32 v123, v123, v89
	s_waitcnt lgkmcnt(11)
	v_mfma_f32_32x32x16_bf16 v[46:61], v[206:209], v[8:11], v[46:61]
	ds_read_b64_tr_b16 v[206:207], v159 offset:36864
	ds_read_b64_tr_b16 v[208:209], v159 offset:37376
	v_add_f32_e32 v122, v122, v90
	v_add_f32_e32 v123, v123, v91
	v_add_f32_e32 v122, v122, v92
	v_add_f32_e32 v123, v123, v93
	v_cvt_pk_bf16_f32 v230, v86, v87
	v_cvt_pk_bf16_f32 v231, v88, v89
	v_cvt_pk_bf16_f32 v232, v90, v91
	v_cvt_pk_bf16_f32 v233, v92, v93
	v_sub_f32_e32 v94, v94, v160
	v_sub_f32_e32 v95, v95, v160
	v_sub_f32_e32 v96, v96, v160
	s_waitcnt lgkmcnt(12)
	v_mfma_f32_32x32x16_bf16 v[62:77], v[210:213], v[8:11], v[62:77]
	ds_read_b64_tr_b16 v[210:211], v159 offset:40960
	ds_read_b64_tr_b16 v[212:213], v159 offset:41472
	v_sub_f32_e32 v97, v97, v160
	v_sub_f32_e32 v98, v98, v160
	v_sub_f32_e32 v99, v99, v160
	v_sub_f32_e32 v100, v100, v160
	v_sub_f32_e32 v101, v101, v160
	v_exp_f32_e32 v94, v94
	v_exp_f32_e32 v95, v95
	v_exp_f32_e32 v96, v96
	v_exp_f32_e32 v97, v97
	v_exp_f32_e32 v98, v98
	v_exp_f32_e32 v99, v99
	s_waitcnt lgkmcnt(13)
	v_mfma_f32_32x32x16_bf16 v[46:61], v[214:217], v[110:113], v[46:61]
	ds_read_b64_tr_b16 v[214:215], v159 offset:37888
	ds_read_b64_tr_b16 v[216:217], v159 offset:38400
	v_exp_f32_e32 v100, v100
	v_exp_f32_e32 v101, v101
	v_add_f32_e32 v122, v122, v94
	v_add_f32_e32 v123, v123, v95
	v_add_f32_e32 v122, v122, v96
	v_add_f32_e32 v123, v123, v97
	v_add_f32_e32 v122, v122, v98
	v_add_f32_e32 v123, v123, v99
	v_add_f32_e32 v122, v122, v100
	v_add_f32_e32 v123, v123, v101
	v_cvt_pk_bf16_f32 v234, v94, v95
	s_waitcnt lgkmcnt(14)
	v_mfma_f32_32x32x16_bf16 v[62:77], v[222:225], v[110:113], v[62:77]
	s_waitcnt lgkmcnt(13)
	ds_read_b64_tr_b16 v[222:223], v159 offset:41984
	ds_read_b64_tr_b16 v[224:225], v159 offset:42496
	v_cvt_pk_bf16_f32 v235, v96, v97
	v_cvt_pk_bf16_f32 v236, v98, v99
	v_cvt_pk_bf16_f32 v237, v100, v101
	v_sub_f32_e32 v102, v102, v160
	v_sub_f32_e32 v103, v103, v160
	v_sub_f32_e32 v104, v104, v160
	v_sub_f32_e32 v105, v105, v160
	v_sub_f32_e32 v106, v106, v160
	v_sub_f32_e32 v107, v107, v160
	v_sub_f32_e32 v108, v108, v160
	v_sub_f32_e32 v109, v109, v160
	s_waitcnt lgkmcnt(8)
	s_waitcnt vmcnt(0)
	ds_write_b128 v162, v[114:117] offset:13312
	s_and_saveexec_b64 s[12:13], s[6:7]
	s_cbranch_execz .Lf3_nocwt1FULL
	v_xor_b32_e32 v152, 0x80000000, v152
	ds_write_b32 v154, v152 offset:43264

.Lf3_tail2:
	s_cmp_ge_u32 s11, 2
	s_cbranch_scc1 .Lf3_t2_FULL
	s_cmp_eq_u32 s11, 1
	s_cbranch_scc1 .Lf3_t2_FULLM
	v_add_f32_e32 v127, 0x41800000, v160
	v_cmp_gt_f32_e32 vcc, v126, v127
	s_cbranch_vccnz .Lf3_resct2CONLY
.Lf3_resc_rett2CONLY:
	s_waitcnt lgkmcnt(0)
	ds_read_b64_tr_b16 v[190:191], v159 offset:26624
	ds_read_b64_tr_b16 v[192:193], v159 offset:27136
	ds_read_b64_tr_b16 v[194:195], v159 offset:30720
	ds_read_b64_tr_b16 v[196:197], v159 offset:31232
	ds_read_b64_tr_b16 v[198:199], v159 offset:27648
	ds_read_b64_tr_b16 v[200:201], v159 offset:28160
	ds_read_b64_tr_b16 v[202:203], v159 offset:31744
	ds_read_b64_tr_b16 v[204:205], v159 offset:32256
	ds_read_b64_tr_b16 v[206:207], v159 offset:28672
	ds_read_b64_tr_b16 v[208:209], v159 offset:29184
	ds_read_b64_tr_b16 v[210:211], v159 offset:32768
	ds_read_b64_tr_b16 v[212:213], v159 offset:33280
	ds_read_b64_tr_b16 v[214:215], v159 offset:29696
	ds_read_b64_tr_b16 v[216:217], v159 offset:30208
	v_sub_f32_e32 v46, v46, v160
	v_sub_f32_e32 v47, v47, v160
	v_sub_f32_e32 v48, v48, v160
	v_sub_f32_e32 v49, v49, v160
	v_sub_f32_e32 v50, v50, v160
	v_sub_f32_e32 v51, v51, v160
	v_sub_f32_e32 v52, v52, v160
	v_sub_f32_e32 v53, v53, v160
	v_exp_f32_e32 v46, v46
	v_exp_f32_e32 v47, v47
	v_exp_f32_e32 v48, v48
	v_exp_f32_e32 v49, v49
	v_exp_f32_e32 v50, v50
	v_exp_f32_e32 v51, v51
	v_exp_f32_e32 v52, v52
	v_exp_f32_e32 v53, v53
	v_add_f32_e32 v122, v46, v47
	v_add_f32_e32 v123, v48, v49
	v_add_f32_e32 v122, v122, v50
	v_add_f32_e32 v123, v123, v51
	v_add_f32_e32 v122, v122, v52
	v_add_f32_e32 v123, v123, v53
	v_cvt_pk_bf16_f32 v226, v46, v47
	v_cvt_pk_bf16_f32 v227, v48, v49
	v_cvt_pk_bf16_f32 v228, v50, v51
	v_cvt_pk_bf16_f32 v229, v52, v53
	v_sub_f32_e32 v54, v54, v160
	v_sub_f32_e32 v55, v55, v160
	v_sub_f32_e32 v56, v56, v160
	v_sub_f32_e32 v57, v57, v160
	v_sub_f32_e32 v58, v58, v160
	v_sub_f32_e32 v59, v59, v160
	v_sub_f32_e32 v60, v60, v160
	v_sub_f32_e32 v61, v61, v160
	v_exp_f32_e32 v54, v54
	v_exp_f32_e32 v55, v55
	v_exp_f32_e32 v56, v56
	v_exp_f32_e32 v57, v57
	v_exp_f32_e32 v58, v58
	v_exp_f32_e32 v59, v59
	v_exp_f32_e32 v60, v60
	v_exp_f32_e32 v61, v61
	v_add_f32_e32 v122, v122, v54
	v_add_f32_e32 v123, v123, v55
	v_add_f32_e32 v122, v122, v56
	v_add_f32_e32 v123, v123, v57
	v_add_f32_e32 v122, v122, v58
	v_add_f32_e32 v123, v123, v59
	v_add_f32_e32 v122, v122, v60
	v_add_f32_e32 v123, v123, v61
	v_cvt_pk_bf16_f32 v230, v54, v55
	v_cvt_pk_bf16_f32 v231, v56, v57
	v_cvt_pk_bf16_f32 v232, v58, v59
	v_cvt_pk_bf16_f32 v233, v60, v61
	v_sub_f32_e32 v62, v62, v160
	v_sub_f32_e32 v63, v63, v160
	v_sub_f32_e32 v64, v64, v160
	v_sub_f32_e32 v65, v65, v160
	v_sub_f32_e32 v66, v66, v160
	v_sub_f32_e32 v67, v67, v160
	v_sub_f32_e32 v68, v68, v160
	v_sub_f32_e32 v69, v69, v160
	v_exp_f32_e32 v62, v62
	v_exp_f32_e32 v63, v63
	v_exp_f32_e32 v64, v64
	v_exp_f32_e32 v65, v65
	v_exp_f32_e32 v66, v66
	v_exp_f32_e32 v67, v67
	v_exp_f32_e32 v68, v68
	v_exp_f32_e32 v69, v69
	v_add_f32_e32 v122, v122, v62
	v_add_f32_e32 v123, v123, v63
	v_add_f32_e32 v122, v122, v64
	v_add_f32_e32 v123, v123, v65
	v_add_f32_e32 v122, v122, v66
	v_add_f32_e32 v123, v123, v67
	v_add_f32_e32 v122, v122, v68
	v_add_f32_e32 v123, v123, v69
	v_cvt_pk_bf16_f32 v234, v62, v63
	v_cvt_pk_bf16_f32 v235, v64, v65
	v_cvt_pk_bf16_f32 v236, v66, v67
	v_cvt_pk_bf16_f32 v237, v68, v69
	v_sub_f32_e32 v70, v70, v160
	v_sub_f32_e32 v71, v71, v160
	v_sub_f32_e32 v72, v72, v160
	v_sub_f32_e32 v73, v73, v160
	v_sub_f32_e32 v74, v74, v160
	v_sub_f32_e32 v75, v75, v160
	v_sub_f32_e32 v76, v76, v160
	v_sub_f32_e32 v77, v77, v160
	v_exp_f32_e32 v70, v70
	v_exp_f32_e32 v71, v71
	v_exp_f32_e32 v72, v72
	v_exp_f32_e32 v73, v73
	v_exp_f32_e32 v74, v74
	v_exp_f32_e32 v75, v75
	v_exp_f32_e32 v76, v76
	v_exp_f32_e32 v77, v77
	v_add_f32_e32 v122, v122, v70
	v_add_f32_e32 v123, v123, v71
	v_add_f32_e32 v122, v122, v72
	v_add_f32_e32 v123, v123, v73
	v_add_f32_e32 v122, v122, v74
	v_add_f32_e32 v123, v123, v75
	v_add_f32_e32 v122, v122, v76
	v_add_f32_e32 v123, v123, v77
	v_cvt_pk_bf16_f32 v238, v70, v71
	v_cvt_pk_bf16_f32 v239, v72, v73
	v_cvt_pk_bf16_f32 v240, v74, v75
	v_cvt_pk_bf16_f32 v241, v76, v77
	v_add_f32_e32 v122, v122, v123
	v_add_f32_e32 v161, v161, v122
	s_waitcnt lgkmcnt(8)
	ds_read_b64_tr_b16 v[222:223], v159 offset:33792
	ds_read_b64_tr_b16 v[224:225], v159 offset:34304
	s_waitcnt vmcnt(0)
	ds_write_b128 v162, v[114:117]
	s_and_saveexec_b64 s[12:13], s[6:7]
	s_cbranch_execz .Lf3_nocwt2CONLY
	v_xor_b32_e32 v152, 0x80000000, v152
	ds_write_b32 v154, v152 offset:43008
.Lf3_nocwt2CONLY:
	s_or_b64 exec, exec, s[12:13]
	ds_write_b128 v155, v[118:121] offset:34816
	s_waitcnt lgkmcnt(0)
	s_barrier
	v_mfma_f32_32x32x16_bf16 v[14:29], v[190:193], v[226:229], v[14:29]
	v_mfma_f32_32x32x16_bf16 v[30:45], v[194:197], v[226:229], v[30:45]
	global_load_dwordx4 v[114:117], v[242:243], off
	s_and_saveexec_b64 s[12:13], s[6:7]
	s_cbranch_execz .Lf3_nockt2CONLY
	global_load_dword v152, v[250:251], off
.Lf3_nockt2CONLY:
	s_or_b64 exec, exec, s[12:13]
	global_load_dwordx4 v[118:121], v[246:247], off
	v_mfma_f32_32x32x16_bf16 v[14:29], v[198:201], v[230:233], v[14:29]
	v_mfma_f32_32x32x16_bf16 v[30:45], v[202:205], v[230:233], v[30:45]
	v_mfma_f32_32x32x16_bf16 v[14:29], v[206:209], v[234:237], v[14:29]
	v_mfma_f32_32x32x16_bf16 v[30:45], v[210:213], v[234:237], v[30:45]
	v_mfma_f32_32x32x16_bf16 v[14:29], v[214:217], v[238:241], v[14:29]
	v_mfma_f32_32x32x16_bf16 v[30:45], v[222:225], v[238:241], v[30:45]
	v_lshl_add_u64 v[242:243], v[242:243], 0, s[46:47]
	v_lshl_add_u64 v[246:247], v[246:247], 0, s[46:47]
	s_branch .Lf3_tail3

.Lf3_nockt2FULL:
	s_or_b64 exec, exec, s[12:13]
	global_load_dwordx4 v[118:121], v[246:247], off
	v_max3_f32 v125, v125, v86, v87
	v_max3_f32 v124, v124, v88, v89
	v_max3_f32 v125, v125, v90, v91
	v_mfma_f32_32x32x16_bf16 v[14:29], v[198:201], v[230:233], v[14:29]
	ds_read_b128 v[198:201], v218 offset:32
	v_max3_f32 v124, v124, v92, v93
	v_max3_f32 v125, v125, v94, v95
	v_max3_f32 v124, v124, v96, v97
	v_mfma_f32_32x32x16_bf16 v[30:45], v[202:205], v[230:233], v[30:45]
	ds_read_b128 v[202:205], v218 offset:4640
	v_max3_f32 v125, v125, v98, v99
	v_max3_f32 v124, v124, v100, v101
	v_max3_f32 v125, v125, v102, v103
	v_mfma_f32_32x32x16_bf16 v[14:29], v[206:209], v[234:237], v[14:29]
	ds_read_b128 v[206:209], v218 offset:64
	v_max3_f32 v124, v124, v104, v105
	v_max3_f32 v125, v125, v106, v107
	v_mfma_f32_32x32x16_bf16 v[30:45], v[210:213], v[234:237], v[30:45]
	ds_read_b128 v[210:213], v218 offset:4672
	v_max3_f32 v124, v124, v108, v109
	v_max_f32_e32 v124, v124, v125
	v_mfma_f32_32x32x16_bf16 v[14:29], v[214:217], v[238:241], v[14:29]
	ds_read_b128 v[214:217], v218 offset:96
	v_mov_b32_e32 v125, v124
	s_nop 1
	v_mfma_f32_32x32x16_bf16 v[30:45], v[222:225], v[238:241], v[30:45]
	s_waitcnt lgkmcnt(14)
	ds_read_b128 v[222:225], v218 offset:4704
	v_permlane32_swap_b32_e32 v124, v125
	v_max_f32_e32 v126, v124, v125
	v_lshl_add_u64 v[242:243], v[242:243], 0, s[46:47]
	v_lshl_add_u64 v[246:247], v[246:247], 0, s[46:47]
	s_branch .Lf3_tail3

.Lf3_nocwt2FULLM:
	s_or_b64 exec, exec, s[12:13]
	ds_write_b128 v155, v[118:121] offset:34816
	v_exp_f32_e32 v70, v70
	v_exp_f32_e32 v71, v71
	v_exp_f32_e32 v72, v72
	v_exp_f32_e32 v73, v73
	v_exp_f32_e32 v74, v74
	v_exp_f32_e32 v75, v75
	v_exp_f32_e32 v76, v76
	v_exp_f32_e32 v77, v77
	v_add_f32_e32 v122, v122, v70
	v_add_f32_e32 v123, v123, v71
	v_add_f32_e32 v122, v122, v72
	v_add_f32_e32 v123, v123, v73
	v_add_f32_e32 v122, v122, v74
	v_add_f32_e32 v123, v123, v75
	v_add_f32_e32 v122, v122, v76
	v_add_f32_e32 v123, v123, v77
	v_cvt_pk_bf16_f32 v238, v70, v71
	v_cvt_pk_bf16_f32 v239, v72, v73
	v_cvt_pk_bf16_f32 v240, v74, v75
	v_cvt_pk_bf16_f32 v241, v76, v77
	v_add_f32_e32 v122, v122, v123
	v_add_f32_e32 v161, v161, v122
	s_waitcnt lgkmcnt(0)
	s_barrier
	ds_read_b128 v[46:49], v158 offset:43008
	ds_read_b128 v[50:53], v158 offset:43040
	ds_read_b128 v[54:57], v158 offset:43072
	ds_read_b128 v[58:61], v158 offset:43104
	ds_read_b128 v[62:65], v158 offset:43136
	ds_read_b128 v[66:69], v158 offset:43168
	ds_read_b128 v[70:73], v158 offset:43200
	ds_read_b128 v[74:77], v158 offset:43232
	v_mfma_f32_32x32x16_bf16 v[14:29], v[190:193], v[226:229], v[14:29]
	ds_read_b128 v[190:193], v218
	v_cmp_le_i32_e64 s[52:53], 0, v219
	v_cmp_le_i32_e64 s[14:15], 32, v219
	v_cmp_le_i32_e64 s[16:17], 1, v219
	v_cndmask_b32_e64 v78, v220, v78, s[52:53]
	v_cmp_le_i32_e64 s[52:53], 33, v219
	v_cndmask_b32_e64 v94, v220, v94, s[14:15]
	v_cmp_le_i32_e64 s[14:15], 2, v219
	v_cndmask_b32_e64 v79, v220, v79, s[16:17]
	v_cmp_le_i32_e64 s[16:17], 34, v219
	v_cndmask_b32_e64 v95, v220, v95, s[52:53]
	v_cmp_le_i32_e64 s[52:53], 3, v219
	v_mfma_f32_32x32x16_bf16 v[30:45], v[194:197], v[226:229], v[30:45]
	ds_read_b128 v[194:197], v218 offset:4608
	global_load_dwordx4 v[114:117], v[242:243], off
	s_and_saveexec_b64 s[12:13], s[6:7]
	s_cbranch_execz .Lf3_nockt2FULLM
	global_load_dword v152, v[250:251], off
.Lf3_nockt2FULLM:
	s_or_b64 exec, exec, s[12:13]
	global_load_dwordx4 v[118:121], v[246:247], off
	v_cndmask_b32_e64 v80, v220, v80, s[14:15]
	v_cmp_le_i32_e64 s[14:15], 35, v219
	v_cndmask_b32_e64 v96, v220, v96, s[16:17]
	v_cmp_le_i32_e64 s[16:17], 8, v219
	v_cndmask_b32_e64 v81, v220, v81, s[52:53]
	v_cmp_le_i32_e64 s[52:53], 40, v219
	v_cndmask_b32_e64 v97, v220, v97, s[14:15]
	v_cmp_le_i32_e64 s[14:15], 9, v219
	v_cndmask_b32_e64 v82, v220, v82, s[16:17]
	v_cmp_le_i32_e64 s[16:17], 41, v219
	v_cndmask_b32_e64 v98, v220, v98, s[52:53]
	v_mfma_f32_32x32x16_bf16 v[14:29], v[198:201], v[230:233], v[14:29]
	ds_read_b128 v[198:201], v218 offset:32
	v_cmp_le_i32_e64 s[52:53], 10, v219
	v_cndmask_b32_e64 v83, v220, v83, s[14:15]
	v_cmp_le_i32_e64 s[14:15], 42, v219
	v_cndmask_b32_e64 v99, v220, v99, s[16:17]
	v_cmp_le_i32_e64 s[16:17], 11, v219
	v_cndmask_b32_e64 v84, v220, v84, s[52:53]
	v_cmp_le_i32_e64 s[52:53], 43, v219
	v_cndmask_b32_e64 v100, v220, v100, s[14:15]
	v_cmp_le_i32_e64 s[14:15], 16, v219
	v_cndmask_b32_e64 v85, v220, v85, s[16:17]
	v_cmp_le_i32_e64 s[16:17], 48, v219
	v_mfma_f32_32x32x16_bf16 v[30:45], v[202:205], v[230:233], v[30:45]
	ds_read_b128 v[202:205], v218 offset:4640
	v_cndmask_b32_e64 v101, v220, v101, s[52:53]
	v_cmp_le_i32_e64 s[52:53], 17, v219
	v_cndmask_b32_e64 v86, v220, v86, s[14:15]
	v_cmp_le_i32_e64 s[14:15], 49, v219
	v_cndmask_b32_e64 v102, v220, v102, s[16:17]
	v_cmp_le_i32_e64 s[16:17], 18, v219
	v_cndmask_b32_e64 v87, v220, v87, s[52:53]
	v_cmp_le_i32_e64 s[52:53], 50, v219
	v_cndmask_b32_e64 v103, v220, v103, s[14:15]
	v_cmp_le_i32_e64 s[14:15], 19, v219
	v_cndmask_b32_e64 v88, v220, v88, s[16:17]
	v_mfma_f32_32x32x16_bf16 v[14:29], v[206:209], v[234:237], v[14:29]
	ds_read_b128 v[206:209], v218 offset:64
	v_cmp_le_i32_e64 s[16:17], 51, v219
	v_cndmask_b32_e64 v104, v220, v104, s[52:53]
	v_cmp_le_i32_e64 s[52:53], 24, v219
	v_cndmask_b32_e64 v89, v220, v89, s[14:15]
	v_cmp_le_i32_e64 s[14:15], 56, v219
	v_cndmask_b32_e64 v105, v220, v105, s[16:17]
	v_cmp_le_i32_e64 s[16:17], 25, v219
	v_cndmask_b32_e64 v90, v220, v90, s[52:53]
	v_cmp_le_i32_e64 s[52:53], 57, v219
	v_cndmask_b32_e64 v106, v220, v106, s[14:15]
	v_mfma_f32_32x32x16_bf16 v[30:45], v[210:213], v[234:237], v[30:45]
	ds_read_b128 v[210:213], v218 offset:4672
	v_cmp_le_i32_e64 s[14:15], 26, v219
	v_cndmask_b32_e64 v91, v220, v91, s[16:17]
	v_cmp_le_i32_e64 s[16:17], 58, v219
	v_cndmask_b32_e64 v107, v220, v107, s[52:53]
	v_cmp_le_i32_e64 s[52:53], 27, v219
	v_cndmask_b32_e64 v92, v220, v92, s[14:15]
	v_cmp_le_i32_e64 s[14:15], 59, v219
	v_cndmask_b32_e64 v108, v220, v108, s[16:17]
	v_cndmask_b32_e64 v93, v220, v93, s[52:53]
	v_cndmask_b32_e64 v109, v220, v109, s[14:15]
	v_mfma_f32_32x32x16_bf16 v[14:29], v[214:217], v[238:241], v[14:29]
	ds_read_b128 v[214:217], v218 offset:96
	v_max3_f32 v124, v78, v79, v80
	v_max3_f32 v125, v81, v82, v83
	v_max3_f32 v124, v124, v84, v85
	v_max3_f32 v125, v125, v86, v87
	v_max3_f32 v124, v124, v88, v89
	v_max3_f32 v125, v125, v90, v91
	v_max3_f32 v124, v124, v92, v93
	v_max3_f32 v125, v125, v94, v95
	v_max3_f32 v124, v124, v96, v97
	v_max3_f32 v125, v125, v98, v99
	v_mfma_f32_32x32x16_bf16 v[30:45], v[222:225], v[238:241], v[30:45]
	s_waitcnt lgkmcnt(14)
	ds_read_b128 v[222:225], v218 offset:4704
	v_max3_f32 v124, v124, v100, v101
	v_max3_f32 v125, v125, v102, v103
	v_max3_f32 v124, v124, v104, v105
	v_max3_f32 v125, v125, v106, v107
	v_max3_f32 v124, v124, v108, v109
	v_max_f32_e32 v124, v124, v125
	v_mov_b32_e32 v125, v124
	s_nop 1
	v_permlane32_swap_b32_e32 v124, v125
	v_max_f32_e32 v126, v124, v125
	v_lshl_add_u64 v[242:243], v[242:243], 0, s[46:47]
	v_lshl_add_u64 v[246:247], v[246:247], 0, s[46:47]
.Lf3_tail3:
	s_cmp_ge_u32 s11, 3
	s_cbranch_scc1 .Lf3_t3_FULL
	s_cmp_eq_u32 s11, 2
	s_cbranch_scc1 .Lf3_t3_FULLM
	s_cmp_eq_u32 s11, 1
	s_cbranch_scc1 .Lf3_t3_CONLY
	s_waitcnt lgkmcnt(0)
	s_waitcnt vmcnt(0)
	ds_write_b128 v162, v[114:117] offset:13312
	s_and_saveexec_b64 s[12:13], s[6:7]
	s_cbranch_execz .Lf3_nocwt3IDLE
	v_xor_b32_e32 v152, 0x80000000, v152
	ds_write_b32 v154, v152 offset:43264
.Lf3_nocwt3IDLE:
	s_or_b64 exec, exec, s[12:13]
	ds_write_b128 v155, v[118:121] offset:26624
	s_waitcnt lgkmcnt(0)
	s_barrier
	global_load_dwordx4 v[118:121], v[248:249], off
	v_lshl_add_u64 v[244:245], v[244:245], 0, s[46:47]
	v_lshl_add_u64 v[248:249], v[248:249], 0, s[46:47]
	v_lshl_add_u64 v[250:251], v[250:251], 0, s[48:49]
	s_branch .Lf3_tail4
.Lf3_t3_FULL:
	v_add_f32_e32 v127, 0x41800000, v160
	v_cmp_gt_f32_e32 vcc, v126, v127
	s_cbranch_vccnz .Lf3_resct3FULL
.Lf3_resc_rett3FULL:
	s_waitcnt lgkmcnt(7)
	v_mfma_f32_32x32x16_bf16 v[46:61], v[190:193], v[0:3], v[46:61]
	ds_read_b64_tr_b16 v[190:191], v159 offset:34816
	ds_read_b64_tr_b16 v[192:193], v159 offset:35328
	v_sub_f32_e32 v78, v78, v160
	v_sub_f32_e32 v79, v79, v160
	v_sub_f32_e32 v80, v80, v160
	v_sub_f32_e32 v81, v81, v160
	v_sub_f32_e32 v82, v82, v160
	v_sub_f32_e32 v83, v83, v160
	v_sub_f32_e32 v84, v84, v160
	v_sub_f32_e32 v85, v85, v160
	v_exp_f32_e32 v78, v78
	v_exp_f32_e32 v79, v79
	v_exp_f32_e32 v80, v80
	v_exp_f32_e32 v81, v81
	s_waitcnt lgkmcnt(8)
	v_mfma_f32_32x32x16_bf16 v[62:77], v[194:197], v[0:3], v[62:77]
	ds_read_b64_tr_b16 v[194:195], v159 offset:38912
	ds_read_b64_tr_b16 v[196:197], v159 offset:39424
	v_exp_f32_e32 v82, v82
	v_exp_f32_e32 v83, v83
	v_exp_f32_e32 v84, v84
	v_exp_f32_e32 v85, v85
	v_add_f32_e32 v122, v78, v79
	v_add_f32_e32 v123, v80, v81
	v_add_f32_e32 v122, v122, v82
	v_add_f32_e32 v123, v123, v83
	v_add_f32_e32 v122, v122, v84
	v_add_f32_e32 v123, v123, v85
	v_cvt_pk_bf16_f32 v226, v78, v79
	v_cvt_pk_bf16_f32 v227, v80, v81
	s_waitcnt lgkmcnt(9)
	v_mfma_f32_32x32x16_bf16 v[46:61], v[198:201], v[4:7], v[46:61]
	ds_read_b64_tr_b16 v[198:199], v159 offset:35840
	ds_read_b64_tr_b16 v[200:201], v159 offset:36352
	v_cvt_pk_bf16_f32 v228, v82, v83
	v_cvt_pk_bf16_f32 v229, v84, v85
	v_sub_f32_e32 v86, v86, v160
	v_sub_f32_e32 v87, v87, v160
	v_sub_f32_e32 v88, v88, v160
	v_sub_f32_e32 v89, v89, v160
	v_sub_f32_e32 v90, v90, v160
	v_sub_f32_e32 v91, v91, v160
	v_sub_f32_e32 v92, v92, v160
	v_sub_f32_e32 v93, v93, v160
	v_exp_f32_e32 v86, v86
	s_waitcnt lgkmcnt(10)
	v_mfma_f32_32x32x16_bf16 v[62:77], v[202:205], v[4:7], v[62:77]
	ds_read_b64_tr_b16 v[202:203], v159 offset:39936
	ds_read_b64_tr_b16 v[204:205], v159 offset:40448
	v_exp_f32_e32 v87, v87
	v_exp_f32_e32 v88, v88
	v_exp_f32_e32 v89, v89
	v_exp_f32_e32 v90, v90
	v_exp_f32_e32 v91, v91
	v_exp_f32_e32 v92, v92
	v_exp_f32_e32 v93, v93
	v_add_f32_e32 v122, v122, v86
	v_add_f32_e32 v123, v123, v87
	v_add_f32_e32 v122, v122, v88
	v_add_f32_e32 v123, v123, v89
	s_waitcnt lgkmcnt(11)
	v_mfma_f32_32x32x16_bf16 v[46:61], v[206:209], v[8:11], v[46:61]
	ds_read_b64_tr_b16 v[206:207], v159 offset:36864
	ds_read_b64_tr_b16 v[208:209], v159 offset:37376
	v_add_f32_e32 v122, v122, v90
	v_add_f32_e32 v123, v123, v91
	v_add_f32_e32 v122, v122, v92
	v_add_f32_e32 v123, v123, v93
	v_cvt_pk_bf16_f32 v230, v86, v87
	v_cvt_pk_bf16_f32 v231, v88, v89
	v_cvt_pk_bf16_f32 v232, v90, v91
	v_cvt_pk_bf16_f32 v233, v92, v93
	v_sub_f32_e32 v94, v94, v160
	v_sub_f32_e32 v95, v95, v160
	v_sub_f32_e32 v96, v96, v160
	s_waitcnt lgkmcnt(12)
	v_mfma_f32_32x32x16_bf16 v[62:77], v[210:213], v[8:11], v[62:77]
	ds_read_b64_tr_b16 v[210:211], v159 offset:40960
	ds_read_b64_tr_b16 v[212:213], v159 offset:41472
	v_sub_f32_e32 v97, v97, v160
	v_sub_f32_e32 v98, v98, v160
	v_sub_f32_e32 v99, v99, v160
	v_sub_f32_e32 v100, v100, v160
	v_sub_f32_e32 v101, v101, v160
	v_exp_f32_e32 v94, v94
	v_exp_f32_e32 v95, v95
	v_exp_f32_e32 v96, v96
	v_exp_f32_e32 v97, v97
	v_exp_f32_e32 v98, v98
	v_exp_f32_e32 v99, v99
	s_waitcnt lgkmcnt(13)
	v_mfma_f32_32x32x16_bf16 v[46:61], v[214:217], v[110:113], v[46:61]
	ds_read_b64_tr_b16 v[214:215], v159 offset:37888
	ds_read_b64_tr_b16 v[216:217], v159 offset:38400
	v_exp_f32_e32 v100, v100
	v_exp_f32_e32 v101, v101
	v_add_f32_e32 v122, v122, v94
	v_add_f32_e32 v123, v123, v95
	v_add_f32_e32 v122, v122, v96
	v_add_f32_e32 v123, v123, v97
	v_add_f32_e32 v122, v122, v98
	v_add_f32_e32 v123, v123, v99
	v_add_f32_e32 v122, v122, v100
	v_add_f32_e32 v123, v123, v101
	v_cvt_pk_bf16_f32 v234, v94, v95
	s_waitcnt lgkmcnt(14)
	v_mfma_f32_32x32x16_bf16 v[62:77], v[222:225], v[110:113], v[62:77]
	s_waitcnt lgkmcnt(13)
	ds_read_b64_tr_b16 v[222:223], v159 offset:41984
	ds_read_b64_tr_b16 v[224:225], v159 offset:42496
	v_cvt_pk_bf16_f32 v235, v96, v97
	v_cvt_pk_bf16_f32 v236, v98, v99
	v_cvt_pk_bf16_f32 v237, v100, v101
	v_sub_f32_e32 v102, v102, v160
	v_sub_f32_e32 v103, v103, v160
	v_sub_f32_e32 v104, v104, v160
	v_sub_f32_e32 v105, v105, v160
	v_sub_f32_e32 v106, v106, v160
	v_sub_f32_e32 v107, v107, v160
	v_sub_f32_e32 v108, v108, v160
	v_sub_f32_e32 v109, v109, v160
	s_waitcnt lgkmcnt(8)
	s_waitcnt vmcnt(0)
	ds_write_b128 v162, v[114:117] offset:13312
	s_and_saveexec_b64 s[12:13], s[6:7]
	s_cbranch_execz .Lf3_nocwt3FULL
	v_xor_b32_e32 v152, 0x80000000, v152
	ds_write_b32 v154, v152 offset:43264
.Lf3_nocwt3FULL:
	s_or_b64 exec, exec, s[12:13]
	ds_write_b128 v155, v[118:121] offset:26624
	v_exp_f32_e32 v102, v102
	v_exp_f32_e32 v103, v103
	v_exp_f32_e32 v104, v104
	v_exp_f32_e32 v105, v105
	v_exp_f32_e32 v106, v106
	v_exp_f32_e32 v107, v107
	v_exp_f32_e32 v108, v108
	v_exp_f32_e32 v109, v109
	v_add_f32_e32 v122, v122, v102
	v_add_f32_e32 v123, v123, v103
	v_add_f32_e32 v122, v122, v104
	v_add_f32_e32 v123, v123, v105
	v_add_f32_e32 v122, v122, v106
	v_add_f32_e32 v123, v123, v107
	v_add_f32_e32 v122, v122, v108
	v_add_f32_e32 v123, v123, v109
	v_cvt_pk_bf16_f32 v238, v102, v103
	v_cvt_pk_bf16_f32 v239, v104, v105
	v_cvt_pk_bf16_f32 v240, v106, v107
	v_cvt_pk_bf16_f32 v241, v108, v109
	v_add_f32_e32 v122, v122, v123
	v_add_f32_e32 v161, v161, v122
	s_waitcnt lgkmcnt(0)
	s_barrier
	ds_read_b128 v[78:81], v158 offset:43264
	ds_read_b128 v[82:85], v158 offset:43296
	ds_read_b128 v[86:89], v158 offset:43328
	ds_read_b128 v[90:93], v158 offset:43360
	ds_read_b128 v[94:97], v158 offset:43392
	ds_read_b128 v[98:101], v158 offset:43424
	ds_read_b128 v[102:105], v158 offset:43456
	ds_read_b128 v[106:109], v158 offset:43488
	v_mfma_f32_32x32x16_bf16 v[14:29], v[190:193], v[226:229], v[14:29]
	ds_read_b128 v[190:193], v218 offset:13312
	v_max3_f32 v124, v46, v47, v48
	v_max3_f32 v125, v49, v50, v51
	v_max3_f32 v124, v124, v52, v53
	v_mfma_f32_32x32x16_bf16 v[30:45], v[194:197], v[226:229], v[30:45]
	ds_read_b128 v[194:197], v218 offset:17920
	global_load_dwordx4 v[118:121], v[248:249], off
	v_max3_f32 v125, v125, v54, v55
	v_max3_f32 v124, v124, v56, v57
	v_max3_f32 v125, v125, v58, v59
	v_mfma_f32_32x32x16_bf16 v[14:29], v[198:201], v[230:233], v[14:29]
	ds_read_b128 v[198:201], v218 offset:13344
	v_max3_f32 v124, v124, v60, v61
	v_max3_f32 v125, v125, v62, v63
	v_max3_f32 v124, v124, v64, v65
	v_mfma_f32_32x32x16_bf16 v[30:45], v[202:205], v[230:233], v[30:45]
	ds_read_b128 v[202:205], v218 offset:17952
	v_max3_f32 v125, v125, v66, v67
	v_max3_f32 v124, v124, v68, v69
	v_max3_f32 v125, v125, v70, v71
	v_mfma_f32_32x32x16_bf16 v[14:29], v[206:209], v[234:237], v[14:29]
	ds_read_b128 v[206:209], v218 offset:13376
	v_max3_f32 v124, v124, v72, v73
	v_max3_f32 v125, v125, v74, v75
	v_mfma_f32_32x32x16_bf16 v[30:45], v[210:213], v[234:237], v[30:45]
	ds_read_b128 v[210:213], v218 offset:17984
	v_max3_f32 v124, v124, v76, v77
	v_max_f32_e32 v124, v124, v125
	v_mfma_f32_32x32x16_bf16 v[14:29], v[214:217], v[238:241], v[14:29]
	ds_read_b128 v[214:217], v218 offset:13408
	v_mov_b32_e32 v125, v124
	s_nop 1
	v_mfma_f32_32x32x16_bf16 v[30:45], v[222:225], v[238:241], v[30:45]
	s_waitcnt lgkmcnt(14)
	ds_read_b128 v[222:225], v218 offset:18016
	v_permlane32_swap_b32_e32 v124, v125
	v_max_f32_e32 v126, v124, v125
	v_lshl_add_u64 v[244:245], v[244:245], 0, s[46:47]
	v_lshl_add_u64 v[248:249], v[248:249], 0, s[46:47]
	v_lshl_add_u64 v[250:251], v[250:251], 0, s[48:49]
	s_branch .Lf3_tail4
.Lf3_t3_FULLM:
	v_add_f32_e32 v127, 0x41800000, v160
	v_cmp_gt_f32_e32 vcc, v126, v127
	s_cbranch_vccnz .Lf3_resct3FULLM
.Lf3_resc_rett3FULLM:
	s_waitcnt lgkmcnt(7)
	v_mfma_f32_32x32x16_bf16 v[46:61], v[190:193], v[0:3], v[46:61]
	ds_read_b64_tr_b16 v[190:191], v159 offset:34816
	ds_read_b64_tr_b16 v[192:193], v159 offset:35328
	v_sub_f32_e32 v78, v78, v160
	v_sub_f32_e32 v79, v79, v160
	v_sub_f32_e32 v80, v80, v160
	v_sub_f32_e32 v81, v81, v160
	v_sub_f32_e32 v82, v82, v160
	v_sub_f32_e32 v83, v83, v160
	v_sub_f32_e32 v84, v84, v160
	v_sub_f32_e32 v85, v85, v160
	v_exp_f32_e32 v78, v78
	v_exp_f32_e32 v79, v79
	v_exp_f32_e32 v80, v80
	v_exp_f32_e32 v81, v81
	s_waitcnt lgkmcnt(8)
	v_mfma_f32_32x32x16_bf16 v[62:77], v[194:197], v[0:3], v[62:77]
	ds_read_b64_tr_b16 v[194:195], v159 offset:38912
	ds_read_b64_tr_b16 v[196:197], v159 offset:39424
	v_exp_f32_e32 v82, v82
	v_exp_f32_e32 v83, v83
	v_exp_f32_e32 v84, v84
	v_exp_f32_e32 v85, v85
	v_add_f32_e32 v122, v78, v79
	v_add_f32_e32 v123, v80, v81
	v_add_f32_e32 v122, v122, v82
	v_add_f32_e32 v123, v123, v83
	v_add_f32_e32 v122, v122, v84
	v_add_f32_e32 v123, v123, v85
	v_cvt_pk_bf16_f32 v226, v78, v79
	v_cvt_pk_bf16_f32 v227, v80, v81
	s_waitcnt lgkmcnt(9)
	v_mfma_f32_32x32x16_bf16 v[46:61], v[198:201], v[4:7], v[46:61]
	ds_read_b64_tr_b16 v[198:199], v159 offset:35840
	ds_read_b64_tr_b16 v[200:201], v159 offset:36352
	v_cvt_pk_bf16_f32 v228, v82, v83
	v_cvt_pk_bf16_f32 v229, v84, v85
	v_sub_f32_e32 v86, v86, v160
	v_sub_f32_e32 v87, v87, v160
	v_sub_f32_e32 v88, v88, v160
	v_sub_f32_e32 v89, v89, v160
	v_sub_f32_e32 v90, v90, v160
	v_sub_f32_e32 v91, v91, v160
	v_sub_f32_e32 v92, v92, v160
	v_sub_f32_e32 v93, v93, v160
	v_exp_f32_e32 v86, v86
	s_waitcnt lgkmcnt(10)
	v_mfma_f32_32x32x16_bf16 v[62:77], v[202:205], v[4:7], v[62:77]
	ds_read_b64_tr_b16 v[202:203], v159 offset:39936
	ds_read_b64_tr_b16 v[204:205], v159 offset:40448
	v_exp_f32_e32 v87, v87
	v_exp_f32_e32 v88, v88
	v_exp_f32_e32 v89, v89
	v_exp_f32_e32 v90, v90
	v_exp_f32_e32 v91, v91
	v_exp_f32_e32 v92, v92
	v_exp_f32_e32 v93, v93
	v_add_f32_e32 v122, v122, v86
	v_add_f32_e32 v123, v123, v87
	v_add_f32_e32 v122, v122, v88
	v_add_f32_e32 v123, v123, v89
	s_waitcnt lgkmcnt(11)
	v_mfma_f32_32x32x16_bf16 v[46:61], v[206:209], v[8:11], v[46:61]
	ds_read_b64_tr_b16 v[206:207], v159 offset:36864
	ds_read_b64_tr_b16 v[208:209], v159 offset:37376
	v_add_f32_e32 v122, v122, v90
	v_add_f32_e32 v123, v123, v91
	v_add_f32_e32 v122, v122, v92
	v_add_f32_e32 v123, v123, v93
	v_cvt_pk_bf16_f32 v230, v86, v87
	v_cvt_pk_bf16_f32 v231, v88, v89
	v_cvt_pk_bf16_f32 v232, v90, v91
	v_cvt_pk_bf16_f32 v233, v92, v93
	v_sub_f32_e32 v94, v94, v160
	v_sub_f32_e32 v95, v95, v160
	v_sub_f32_e32 v96, v96, v160
	s_waitcnt lgkmcnt(12)
	v_mfma_f32_32x32x16_bf16 v[62:77], v[210:213], v[8:11], v[62:77]
	ds_read_b64_tr_b16 v[210:211], v159 offset:40960
	ds_read_b64_tr_b16 v[212:213], v159 offset:41472
	v_sub_f32_e32 v97, v97, v160
	v_sub_f32_e32 v98, v98, v160
	v_sub_f32_e32 v99, v99, v160
	v_sub_f32_e32 v100, v100, v160
	v_sub_f32_e32 v101, v101, v160
	v_exp_f32_e32 v94, v94
	v_exp_f32_e32 v95, v95
	v_exp_f32_e32 v96, v96
	v_exp_f32_e32 v97, v97
	v_exp_f32_e32 v98, v98
	v_exp_f32_e32 v99, v99
	s_waitcnt lgkmcnt(13)
	v_mfma_f32_32x32x16_bf16 v[46:61], v[214:217], v[110:113], v[46:61]
	ds_read_b64_tr_b16 v[214:215], v159 offset:37888
	ds_read_b64_tr_b16 v[216:217], v159 offset:38400
	v_exp_f32_e32 v100, v100
	v_exp_f32_e32 v101, v101
	v_add_f32_e32 v122, v122, v94
	v_add_f32_e32 v123, v123, v95
	v_add_f32_e32 v122, v122, v96
	v_add_f32_e32 v123, v123, v97
	v_add_f32_e32 v122, v122, v98
	v_add_f32_e32 v123, v123, v99
	v_add_f32_e32 v122, v122, v100
	v_add_f32_e32 v123, v123, v101
	v_cvt_pk_bf16_f32 v234, v94, v95
	s_waitcnt lgkmcnt(14)
	v_mfma_f32_32x32x16_bf16 v[62:77], v[222:225], v[110:113], v[62:77]
	s_waitcnt lgkmcnt(13)
	ds_read_b64_tr_b16 v[222:223], v159 offset:41984
	ds_read_b64_tr_b16 v[224:225], v159 offset:42496
	v_cvt_pk_bf16_f32 v235, v96, v97
	v_cvt_pk_bf16_f32 v236, v98, v99
	v_cvt_pk_bf16_f32 v237, v100, v101
	v_sub_f32_e32 v102, v102, v160
	v_sub_f32_e32 v103, v103, v160
	v_sub_f32_e32 v104, v104, v160
	v_sub_f32_e32 v105, v105, v160
	v_sub_f32_e32 v106, v106, v160
	v_sub_f32_e32 v107, v107, v160
	v_sub_f32_e32 v108, v108, v160
	v_sub_f32_e32 v109, v109, v160
	s_waitcnt lgkmcnt(8)
	s_waitcnt vmcnt(0)
	ds_write_b128 v162, v[114:117] offset:13312
	s_and_saveexec_b64 s[12:13], s[6:7]
	s_cbranch_execz .Lf3_nocwt3FULLM
	v_xor_b32_e32 v152, 0x80000000, v152
	ds_write_b32 v154, v152 offset:43264
.Lf3_nocwt3FULLM:
	s_or_b64 exec, exec, s[12:13]
	ds_write_b128 v155, v[118:121] offset:26624
	v_exp_f32_e32 v102, v102
	v_exp_f32_e32 v103, v103
	v_exp_f32_e32 v104, v104
	v_exp_f32_e32 v105, v105
	v_exp_f32_e32 v106, v106
	v_exp_f32_e32 v107, v107
	v_exp_f32_e32 v108, v108
	v_exp_f32_e32 v109, v109
	v_add_f32_e32 v122, v122, v102
	v_add_f32_e32 v123, v123, v103
	v_add_f32_e32 v122, v122, v104
	v_add_f32_e32 v123, v123, v105
	v_add_f32_e32 v122, v122, v106
	v_add_f32_e32 v123, v123, v107
	v_add_f32_e32 v122, v122, v108
	v_add_f32_e32 v123, v123, v109
	v_cvt_pk_bf16_f32 v238, v102, v103
	v_cvt_pk_bf16_f32 v239, v104, v105
	v_cvt_pk_bf16_f32 v240, v106, v107
	v_cvt_pk_bf16_f32 v241, v108, v109
	v_add_f32_e32 v122, v122, v123
	v_add_f32_e32 v161, v161, v122
	s_waitcnt lgkmcnt(0)
	s_barrier
	ds_read_b128 v[78:81], v158 offset:43264
	ds_read_b128 v[82:85], v158 offset:43296
	ds_read_b128 v[86:89], v158 offset:43328
	ds_read_b128 v[90:93], v158 offset:43360
	ds_read_b128 v[94:97], v158 offset:43392
	ds_read_b128 v[98:101], v158 offset:43424
	ds_read_b128 v[102:105], v158 offset:43456
	ds_read_b128 v[106:109], v158 offset:43488
	v_mfma_f32_32x32x16_bf16 v[14:29], v[190:193], v[226:229], v[14:29]
	ds_read_b128 v[190:193], v218 offset:13312
	v_cmp_le_i32_e64 s[52:53], 0, v219
	v_cmp_le_i32_e64 s[14:15], 32, v219
	v_cmp_le_i32_e64 s[16:17], 1, v219
	v_cndmask_b32_e64 v46, v220, v46, s[52:53]
	v_cmp_le_i32_e64 s[52:53], 33, v219
	v_cndmask_b32_e64 v62, v220, v62, s[14:15]
	v_cmp_le_i32_e64 s[14:15], 2, v219
	v_cndmask_b32_e64 v47, v220, v47, s[16:17]
	v_cmp_le_i32_e64 s[16:17], 34, v219
	v_cndmask_b32_e64 v63, v220, v63, s[52:53]
	v_cmp_le_i32_e64 s[52:53], 3, v219
	v_mfma_f32_32x32x16_bf16 v[30:45], v[194:197], v[226:229], v[30:45]
	ds_read_b128 v[194:197], v218 offset:17920
	global_load_dwordx4 v[118:121], v[248:249], off
	v_cndmask_b32_e64 v48, v220, v48, s[14:15]
	v_cmp_le_i32_e64 s[14:15], 35, v219
	v_cndmask_b32_e64 v64, v220, v64, s[16:17]
	v_cmp_le_i32_e64 s[16:17], 8, v219
	v_cndmask_b32_e64 v49, v220, v49, s[52:53]
	v_cmp_le_i32_e64 s[52:53], 40, v219
	v_cndmask_b32_e64 v65, v220, v65, s[14:15]
	v_cmp_le_i32_e64 s[14:15], 9, v219
	v_cndmask_b32_e64 v50, v220, v50, s[16:17]
	v_cmp_le_i32_e64 s[16:17], 41, v219
	v_cndmask_b32_e64 v66, v220, v66, s[52:53]
	v_mfma_f32_32x32x16_bf16 v[14:29], v[198:201], v[230:233], v[14:29]
	ds_read_b128 v[198:201], v218 offset:13344
	v_cmp_le_i32_e64 s[52:53], 10, v219
	v_cndmask_b32_e64 v51, v220, v51, s[14:15]
	v_cmp_le_i32_e64 s[14:15], 42, v219
	v_cndmask_b32_e64 v67, v220, v67, s[16:17]
	v_cmp_le_i32_e64 s[16:17], 11, v219
	v_cndmask_b32_e64 v52, v220, v52, s[52:53]
	v_cmp_le_i32_e64 s[52:53], 43, v219
	v_cndmask_b32_e64 v68, v220, v68, s[14:15]
	v_cmp_le_i32_e64 s[14:15], 16, v219
	v_cndmask_b32_e64 v53, v220, v53, s[16:17]
	v_cmp_le_i32_e64 s[16:17], 48, v219
	v_mfma_f32_32x32x16_bf16 v[30:45], v[202:205], v[230:233], v[30:45]
	ds_read_b128 v[202:205], v218 offset:17952
	v_cndmask_b32_e64 v69, v220, v69, s[52:53]
	v_cmp_le_i32_e64 s[52:53], 17, v219
	v_cndmask_b32_e64 v54, v220, v54, s[14:15]
	v_cmp_le_i32_e64 s[14:15], 49, v219
	v_cndmask_b32_e64 v70, v220, v70, s[16:17]
	v_cmp_le_i32_e64 s[16:17], 18, v219
	v_cndmask_b32_e64 v55, v220, v55, s[52:53]
	v_cmp_le_i32_e64 s[52:53], 50, v219
	v_cndmask_b32_e64 v71, v220, v71, s[14:15]
	v_cmp_le_i32_e64 s[14:15], 19, v219
	v_cndmask_b32_e64 v56, v220, v56, s[16:17]
	v_mfma_f32_32x32x16_bf16 v[14:29], v[206:209], v[234:237], v[14:29]
	ds_read_b128 v[206:209], v218 offset:13376
	v_cmp_le_i32_e64 s[16:17], 51, v219
	v_cndmask_b32_e64 v72, v220, v72, s[52:53]
	v_cmp_le_i32_e64 s[52:53], 24, v219
	v_cndmask_b32_e64 v57, v220, v57, s[14:15]
	v_cmp_le_i32_e64 s[14:15], 56, v219
	v_cndmask_b32_e64 v73, v220, v73, s[16:17]
	v_cmp_le_i32_e64 s[16:17], 25, v219
	v_cndmask_b32_e64 v58, v220, v58, s[52:53]
	v_cmp_le_i32_e64 s[52:53], 57, v219
	v_cndmask_b32_e64 v74, v220, v74, s[14:15]
	v_mfma_f32_32x32x16_bf16 v[30:45], v[210:213], v[234:237], v[30:45]
	ds_read_b128 v[210:213], v218 offset:17984
	v_cmp_le_i32_e64 s[14:15], 26, v219
	v_cndmask_b32_e64 v59, v220, v59, s[16:17]
	v_cmp_le_i32_e64 s[16:17], 58, v219
	v_cndmask_b32_e64 v75, v220, v75, s[52:53]
	v_cmp_le_i32_e64 s[52:53], 27, v219
	v_cndmask_b32_e64 v60, v220, v60, s[14:15]
	v_cmp_le_i32_e64 s[14:15], 59, v219
	v_cndmask_b32_e64 v76, v220, v76, s[16:17]
	v_cndmask_b32_e64 v61, v220, v61, s[52:53]
	v_cndmask_b32_e64 v77, v220, v77, s[14:15]
	v_mfma_f32_32x32x16_bf16 v[14:29], v[214:217], v[238:241], v[14:29]
	ds_read_b128 v[214:217], v218 offset:13408
	v_max3_f32 v124, v46, v47, v48
	v_max3_f32 v125, v49, v50, v51
	v_max3_f32 v124, v124, v52, v53
	v_max3_f32 v125, v125, v54, v55
	v_max3_f32 v124, v124, v56, v57
	v_max3_f32 v125, v125, v58, v59
	v_max3_f32 v124, v124, v60, v61
	v_max3_f32 v125, v125, v62, v63
	v_max3_f32 v124, v124, v64, v65
	v_max3_f32 v125, v125, v66, v67
	v_mfma_f32_32x32x16_bf16 v[30:45], v[222:225], v[238:241], v[30:45]
	s_waitcnt lgkmcnt(14)
	ds_read_b128 v[222:225], v218 offset:18016
	v_max3_f32 v124, v124, v68, v69
	v_max3_f32 v125, v125, v70, v71
	v_max3_f32 v124, v124, v72, v73
	v_max3_f32 v125, v125, v74, v75
	v_max3_f32 v124, v124, v76, v77
	v_max_f32_e32 v124, v124, v125
	v_mov_b32_e32 v125, v124
	s_nop 1
	v_permlane32_swap_b32_e32 v124, v125
	v_max_f32_e32 v126, v124, v125
	v_lshl_add_u64 v[244:245], v[244:245], 0, s[46:47]
	v_lshl_add_u64 v[248:249], v[248:249], 0, s[46:47]
	v_lshl_add_u64 v[250:251], v[250:251], 0, s[48:49]
	s_branch .Lf3_tail4

.Lf3_resc_rett3CONLY:
	s_waitcnt lgkmcnt(0)
	ds_read_b64_tr_b16 v[190:191], v159 offset:34816
	ds_read_b64_tr_b16 v[192:193], v159 offset:35328
	ds_read_b64_tr_b16 v[194:195], v159 offset:38912
	ds_read_b64_tr_b16 v[196:197], v159 offset:39424
	ds_read_b64_tr_b16 v[198:199], v159 offset:35840
	ds_read_b64_tr_b16 v[200:201], v159 offset:36352
	ds_read_b64_tr_b16 v[202:203], v159 offset:39936
	ds_read_b64_tr_b16 v[204:205], v159 offset:40448
	ds_read_b64_tr_b16 v[206:207], v159 offset:36864
	ds_read_b64_tr_b16 v[208:209], v159 offset:37376
	ds_read_b64_tr_b16 v[210:211], v159 offset:40960
	ds_read_b64_tr_b16 v[212:213], v159 offset:41472
	ds_read_b64_tr_b16 v[214:215], v159 offset:37888
	ds_read_b64_tr_b16 v[216:217], v159 offset:38400
	v_sub_f32_e32 v78, v78, v160
	v_sub_f32_e32 v79, v79, v160
	v_sub_f32_e32 v80, v80, v160
	v_sub_f32_e32 v81, v81, v160
	v_sub_f32_e32 v82, v82, v160
	v_sub_f32_e32 v83, v83, v160
	v_sub_f32_e32 v84, v84, v160
	v_sub_f32_e32 v85, v85, v160
	v_exp_f32_e32 v78, v78
	v_exp_f32_e32 v79, v79
	v_exp_f32_e32 v80, v80
	v_exp_f32_e32 v81, v81
	v_exp_f32_e32 v82, v82
	v_exp_f32_e32 v83, v83
	v_exp_f32_e32 v84, v84
	v_exp_f32_e32 v85, v85
	v_add_f32_e32 v122, v78, v79
	v_add_f32_e32 v123, v80, v81
	v_add_f32_e32 v122, v122, v82
	v_add_f32_e32 v123, v123, v83
	v_add_f32_e32 v122, v122, v84
	v_add_f32_e32 v123, v123, v85
	v_cvt_pk_bf16_f32 v226, v78, v79
	v_cvt_pk_bf16_f32 v227, v80, v81
	v_cvt_pk_bf16_f32 v228, v82, v83
	v_cvt_pk_bf16_f32 v229, v84, v85
	v_sub_f32_e32 v86, v86, v160
	v_sub_f32_e32 v87, v87, v160
	v_sub_f32_e32 v88, v88, v160
	v_sub_f32_e32 v89, v89, v160
	v_sub_f32_e32 v90, v90, v160
	v_sub_f32_e32 v91, v91, v160
	v_sub_f32_e32 v92, v92, v160
	v_sub_f32_e32 v93, v93, v160
	v_exp_f32_e32 v86, v86
	v_exp_f32_e32 v87, v87
	v_exp_f32_e32 v88, v88
	v_exp_f32_e32 v89, v89
	v_exp_f32_e32 v90, v90
	v_exp_f32_e32 v91, v91
	v_exp_f32_e32 v92, v92
	v_exp_f32_e32 v93, v93
	v_add_f32_e32 v122, v122, v86
	v_add_f32_e32 v123, v123, v87
	v_add_f32_e32 v122, v122, v88
	v_add_f32_e32 v123, v123, v89
	v_add_f32_e32 v122, v122, v90
	v_add_f32_e32 v123, v123, v91
	v_add_f32_e32 v122, v122, v92
	v_add_f32_e32 v123, v123, v93
	v_cvt_pk_bf16_f32 v230, v86, v87
	v_cvt_pk_bf16_f32 v231, v88, v89
	v_cvt_pk_bf16_f32 v232, v90, v91
	v_cvt_pk_bf16_f32 v233, v92, v93
	v_sub_f32_e32 v94, v94, v160
	v_sub_f32_e32 v95, v95, v160
	v_sub_f32_e32 v96, v96, v160
	v_sub_f32_e32 v97, v97, v160
	v_sub_f32_e32 v98, v98, v160
	v_sub_f32_e32 v99, v99, v160
	v_sub_f32_e32 v100, v100, v160
	v_sub_f32_e32 v101, v101, v160
	v_exp_f32_e32 v94, v94
	v_exp_f32_e32 v95, v95
	v_exp_f32_e32 v96, v96
	v_exp_f32_e32 v97, v97
	v_exp_f32_e32 v98, v98
	v_exp_f32_e32 v99, v99
	v_exp_f32_e32 v100, v100
	v_exp_f32_e32 v101, v101
	v_add_f32_e32 v122, v122, v94
	v_add_f32_e32 v123, v123, v95
	v_add_f32_e32 v122, v122, v96
	v_add_f32_e32 v123, v123, v97
	v_add_f32_e32 v122, v122, v98
	v_add_f32_e32 v123, v123, v99
	v_add_f32_e32 v122, v122, v100
	v_add_f32_e32 v123, v123, v101
	v_cvt_pk_bf16_f32 v234, v94, v95
	v_cvt_pk_bf16_f32 v235, v96, v97
	v_cvt_pk_bf16_f32 v236, v98, v99
	v_cvt_pk_bf16_f32 v237, v100, v101
	v_sub_f32_e32 v102, v102, v160
	v_sub_f32_e32 v103, v103, v160
	v_sub_f32_e32 v104, v104, v160
	v_sub_f32_e32 v105, v105, v160
	v_sub_f32_e32 v106, v106, v160
	v_sub_f32_e32 v107, v107, v160
	v_sub_f32_e32 v108, v108, v160
	v_sub_f32_e32 v109, v109, v160
	v_exp_f32_e32 v102, v102
	v_exp_f32_e32 v103, v103
	v_exp_f32_e32 v104, v104
	v_exp_f32_e32 v105, v105
	v_exp_f32_e32 v106, v106
	v_exp_f32_e32 v107, v107
	v_exp_f32_e32 v108, v108
	v_exp_f32_e32 v109, v109
	v_add_f32_e32 v122, v122, v102
	v_add_f32_e32 v123, v123, v103
	v_add_f32_e32 v122, v122, v104
	v_add_f32_e32 v123, v123, v105
	v_add_f32_e32 v122, v122, v106
	v_add_f32_e32 v123, v123, v107
	v_add_f32_e32 v122, v122, v108
	v_add_f32_e32 v123, v123, v109
	v_cvt_pk_bf16_f32 v238, v102, v103
	v_cvt_pk_bf16_f32 v239, v104, v105
	v_cvt_pk_bf16_f32 v240, v106, v107
	v_cvt_pk_bf16_f32 v241, v108, v109
	v_add_f32_e32 v122, v122, v123
	v_add_f32_e32 v161, v161, v122
	s_waitcnt lgkmcnt(8)
	ds_read_b64_tr_b16 v[222:223], v159 offset:41984
	ds_read_b64_tr_b16 v[224:225], v159 offset:42496
	s_waitcnt vmcnt(0)
	ds_write_b128 v162, v[114:117] offset:13312
	s_and_saveexec_b64 s[12:13], s[6:7]
	s_cbranch_execz .Lf3_nocwt3CONLY
	v_xor_b32_e32 v152, 0x80000000, v152
	ds_write_b32 v154, v152 offset:43264
.Lf3_nocwt3CONLY:
	s_or_b64 exec, exec, s[12:13]
	ds_write_b128 v155, v[118:121] offset:26624
	s_waitcnt lgkmcnt(0)
	s_barrier
	v_mfma_f32_32x32x16_bf16 v[14:29], v[190:193], v[226:229], v[14:29]
	v_mfma_f32_32x32x16_bf16 v[30:45], v[194:197], v[226:229], v[30:45]
	global_load_dwordx4 v[118:121], v[248:249], off
	v_mfma_f32_32x32x16_bf16 v[14:29], v[198:201], v[230:233], v[14:29]
	v_mfma_f32_32x32x16_bf16 v[30:45], v[202:205], v[230:233], v[30:45]
	v_mfma_f32_32x32x16_bf16 v[14:29], v[206:209], v[234:237], v[14:29]
	v_mfma_f32_32x32x16_bf16 v[30:45], v[210:213], v[234:237], v[30:45]
	v_mfma_f32_32x32x16_bf16 v[14:29], v[214:217], v[238:241], v[14:29]
	v_mfma_f32_32x32x16_bf16 v[30:45], v[222:225], v[238:241], v[30:45]
	v_lshl_add_u64 v[244:245], v[244:245], 0, s[46:47]
	v_lshl_add_u64 v[248:249], v[248:249], 0, s[46:47]
	v_lshl_add_u64 v[250:251], v[250:251], 0, s[48:49]
.Lf3_tail4:
	s_cmp_eq_u32 s11, 3
	s_cbranch_scc1 .Lf3_t4_FULLM
	s_cmp_eq_u32 s11, 2
	s_cbranch_scc1 .Lf3_t4_CONLY
	s_waitcnt lgkmcnt(0)
	s_waitcnt vmcnt(0)
	ds_write_b128 v155, v[118:121] offset:34816
	s_waitcnt lgkmcnt(0)
	s_barrier
	v_lshl_add_u64 v[242:243], v[242:243], 0, s[46:47]
	v_lshl_add_u64 v[246:247], v[246:247], 0, s[46:47]
	s_branch .Lf3_tail5

.Lf3_resc_rett4FULLM:
	s_waitcnt lgkmcnt(7)
	v_mfma_f32_32x32x16_bf16 v[78:93], v[190:193], v[0:3], v[78:93]
	ds_read_b64_tr_b16 v[190:191], v159 offset:26624
	ds_read_b64_tr_b16 v[192:193], v159 offset:27136
	v_sub_f32_e32 v46, v46, v160
	v_sub_f32_e32 v47, v47, v160
	v_sub_f32_e32 v48, v48, v160
	v_sub_f32_e32 v49, v49, v160
	v_sub_f32_e32 v50, v50, v160
	v_sub_f32_e32 v51, v51, v160
	v_sub_f32_e32 v52, v52, v160
	v_sub_f32_e32 v53, v53, v160
	v_exp_f32_e32 v46, v46
	v_exp_f32_e32 v47, v47
	v_exp_f32_e32 v48, v48
	v_exp_f32_e32 v49, v49
	s_waitcnt lgkmcnt(8)
	v_mfma_f32_32x32x16_bf16 v[94:109], v[194:197], v[0:3], v[94:109]
	ds_read_b64_tr_b16 v[194:195], v159 offset:30720
	ds_read_b64_tr_b16 v[196:197], v159 offset:31232
	v_exp_f32_e32 v50, v50
	v_exp_f32_e32 v51, v51
	v_exp_f32_e32 v52, v52
	v_exp_f32_e32 v53, v53
	v_add_f32_e32 v122, v46, v47
	v_add_f32_e32 v123, v48, v49
	v_add_f32_e32 v122, v122, v50
	v_add_f32_e32 v123, v123, v51
	v_add_f32_e32 v122, v122, v52
	v_add_f32_e32 v123, v123, v53
	v_cvt_pk_bf16_f32 v226, v46, v47
	v_cvt_pk_bf16_f32 v227, v48, v49
	s_waitcnt lgkmcnt(9)
	v_mfma_f32_32x32x16_bf16 v[78:93], v[198:201], v[4:7], v[78:93]
	ds_read_b64_tr_b16 v[198:199], v159 offset:27648
	ds_read_b64_tr_b16 v[200:201], v159 offset:28160
	v_cvt_pk_bf16_f32 v228, v50, v51
	v_cvt_pk_bf16_f32 v229, v52, v53
	v_sub_f32_e32 v54, v54, v160
	v_sub_f32_e32 v55, v55, v160
	v_sub_f32_e32 v56, v56, v160
	v_sub_f32_e32 v57, v57, v160
	v_sub_f32_e32 v58, v58, v160
	v_sub_f32_e32 v59, v59, v160
	v_sub_f32_e32 v60, v60, v160
	v_sub_f32_e32 v61, v61, v160
	v_exp_f32_e32 v54, v54
	s_waitcnt lgkmcnt(10)
	v_mfma_f32_32x32x16_bf16 v[94:109], v[202:205], v[4:7], v[94:109]
	ds_read_b64_tr_b16 v[202:203], v159 offset:31744
	ds_read_b64_tr_b16 v[204:205], v159 offset:32256
	v_exp_f32_e32 v55, v55
	v_exp_f32_e32 v56, v56
	v_exp_f32_e32 v57, v57
	v_exp_f32_e32 v58, v58
	v_exp_f32_e32 v59, v59
	v_exp_f32_e32 v60, v60
	v_exp_f32_e32 v61, v61
	v_add_f32_e32 v122, v122, v54
	v_add_f32_e32 v123, v123, v55
	v_add_f32_e32 v122, v122, v56
	v_add_f32_e32 v123, v123, v57
	s_waitcnt lgkmcnt(11)
	v_mfma_f32_32x32x16_bf16 v[78:93], v[206:209], v[8:11], v[78:93]
	ds_read_b64_tr_b16 v[206:207], v159 offset:28672
	ds_read_b64_tr_b16 v[208:209], v159 offset:29184
	v_add_f32_e32 v122, v122, v58
	v_add_f32_e32 v123, v123, v59
	v_add_f32_e32 v122, v122, v60
	v_add_f32_e32 v123, v123, v61
	v_cvt_pk_bf16_f32 v230, v54, v55
	v_cvt_pk_bf16_f32 v231, v56, v57
	v_cvt_pk_bf16_f32 v232, v58, v59
	v_cvt_pk_bf16_f32 v233, v60, v61
	v_sub_f32_e32 v62, v62, v160
	v_sub_f32_e32 v63, v63, v160
	v_sub_f32_e32 v64, v64, v160
	s_waitcnt lgkmcnt(12)
	v_mfma_f32_32x32x16_bf16 v[94:109], v[210:213], v[8:11], v[94:109]
	ds_read_b64_tr_b16 v[210:211], v159 offset:32768
	ds_read_b64_tr_b16 v[212:213], v159 offset:33280
	v_sub_f32_e32 v65, v65, v160
	v_sub_f32_e32 v66, v66, v160
	v_sub_f32_e32 v67, v67, v160
	v_sub_f32_e32 v68, v68, v160
	v_sub_f32_e32 v69, v69, v160
	v_exp_f32_e32 v62, v62
	v_exp_f32_e32 v63, v63
	v_exp_f32_e32 v64, v64
	v_exp_f32_e32 v65, v65
	v_exp_f32_e32 v66, v66
	v_exp_f32_e32 v67, v67
	s_waitcnt lgkmcnt(13)
	v_mfma_f32_32x32x16_bf16 v[78:93], v[214:217], v[110:113], v[78:93]
	ds_read_b64_tr_b16 v[214:215], v159 offset:29696
	ds_read_b64_tr_b16 v[216:217], v159 offset:30208
	v_exp_f32_e32 v68, v68
	v_exp_f32_e32 v69, v69
	v_add_f32_e32 v122, v122, v62
	v_add_f32_e32 v123, v123, v63
	v_add_f32_e32 v122, v122, v64
	v_add_f32_e32 v123, v123, v65
	v_add_f32_e32 v122, v122, v66
	v_add_f32_e32 v123, v123, v67
	v_add_f32_e32 v122, v122, v68
	v_add_f32_e32 v123, v123, v69
	v_cvt_pk_bf16_f32 v234, v62, v63
	s_waitcnt lgkmcnt(14)
	v_mfma_f32_32x32x16_bf16 v[94:109], v[222:225], v[110:113], v[94:109]
	s_waitcnt lgkmcnt(13)
	ds_read_b64_tr_b16 v[222:223], v159 offset:33792
	ds_read_b64_tr_b16 v[224:225], v159 offset:34304
	v_cvt_pk_bf16_f32 v235, v64, v65
	v_cvt_pk_bf16_f32 v236, v66, v67
	v_cvt_pk_bf16_f32 v237, v68, v69
	v_sub_f32_e32 v70, v70, v160
	v_sub_f32_e32 v71, v71, v160
	v_sub_f32_e32 v72, v72, v160
	v_sub_f32_e32 v73, v73, v160
	v_sub_f32_e32 v74, v74, v160
	v_sub_f32_e32 v75, v75, v160
	v_sub_f32_e32 v76, v76, v160
	v_sub_f32_e32 v77, v77, v160
	s_waitcnt lgkmcnt(8)
	s_waitcnt vmcnt(0)
	ds_write_b128 v155, v[118:121] offset:34816
	v_exp_f32_e32 v70, v70
	v_exp_f32_e32 v71, v71
	v_exp_f32_e32 v72, v72
	v_exp_f32_e32 v73, v73
	v_exp_f32_e32 v74, v74
	v_exp_f32_e32 v75, v75
	v_exp_f32_e32 v76, v76
	v_exp_f32_e32 v77, v77
	v_add_f32_e32 v122, v122, v70
	v_add_f32_e32 v123, v123, v71
	v_add_f32_e32 v122, v122, v72
	v_add_f32_e32 v123, v123, v73
	v_add_f32_e32 v122, v122, v74
	v_add_f32_e32 v123, v123, v75
	v_add_f32_e32 v122, v122, v76
	v_add_f32_e32 v123, v123, v77
	v_cvt_pk_bf16_f32 v238, v70, v71
	v_cvt_pk_bf16_f32 v239, v72, v73
	v_cvt_pk_bf16_f32 v240, v74, v75
	v_cvt_pk_bf16_f32 v241, v76, v77
	v_add_f32_e32 v122, v122, v123
	v_add_f32_e32 v161, v161, v122
	s_waitcnt lgkmcnt(0)
	s_barrier
	ds_read_b128 v[46:49], v158 offset:43008
	ds_read_b128 v[50:53], v158 offset:43040
	ds_read_b128 v[54:57], v158 offset:43072
	ds_read_b128 v[58:61], v158 offset:43104
	ds_read_b128 v[62:65], v158 offset:43136
	ds_read_b128 v[66:69], v158 offset:43168
	ds_read_b128 v[70:73], v158 offset:43200
	ds_read_b128 v[74:77], v158 offset:43232
	v_mfma_f32_32x32x16_bf16 v[14:29], v[190:193], v[226:229], v[14:29]
	ds_read_b128 v[190:193], v218
	v_cmp_le_i32_e64 s[52:53], 0, v219
	v_cmp_le_i32_e64 s[14:15], 32, v219
	v_cmp_le_i32_e64 s[16:17], 1, v219
	v_cndmask_b32_e64 v78, v220, v78, s[52:53]
	v_cmp_le_i32_e64 s[52:53], 33, v219
	v_cndmask_b32_e64 v94, v220, v94, s[14:15]
	v_cmp_le_i32_e64 s[14:15], 2, v219
	v_cndmask_b32_e64 v79, v220, v79, s[16:17]
	v_cmp_le_i32_e64 s[16:17], 34, v219
	v_cndmask_b32_e64 v95, v220, v95, s[52:53]
	v_cmp_le_i32_e64 s[52:53], 3, v219
	v_mfma_f32_32x32x16_bf16 v[30:45], v[194:197], v[226:229], v[30:45]
	ds_read_b128 v[194:197], v218 offset:4608
	v_cndmask_b32_e64 v80, v220, v80, s[14:15]
	v_cmp_le_i32_e64 s[14:15], 35, v219
	v_cndmask_b32_e64 v96, v220, v96, s[16:17]
	v_cmp_le_i32_e64 s[16:17], 8, v219
	v_cndmask_b32_e64 v81, v220, v81, s[52:53]
	v_cmp_le_i32_e64 s[52:53], 40, v219
	v_cndmask_b32_e64 v97, v220, v97, s[14:15]
	v_cmp_le_i32_e64 s[14:15], 9, v219
	v_cndmask_b32_e64 v82, v220, v82, s[16:17]
	v_cmp_le_i32_e64 s[16:17], 41, v219
	v_cndmask_b32_e64 v98, v220, v98, s[52:53]
	v_mfma_f32_32x32x16_bf16 v[14:29], v[198:201], v[230:233], v[14:29]
	ds_read_b128 v[198:201], v218 offset:32
	v_cmp_le_i32_e64 s[52:53], 10, v219
	v_cndmask_b32_e64 v83, v220, v83, s[14:15]
	v_cmp_le_i32_e64 s[14:15], 42, v219
	v_cndmask_b32_e64 v99, v220, v99, s[16:17]
	v_cmp_le_i32_e64 s[16:17], 11, v219
	v_cndmask_b32_e64 v84, v220, v84, s[52:53]
	v_cmp_le_i32_e64 s[52:53], 43, v219
	v_cndmask_b32_e64 v100, v220, v100, s[14:15]
	v_cmp_le_i32_e64 s[14:15], 16, v219
	v_cndmask_b32_e64 v85, v220, v85, s[16:17]
	v_cmp_le_i32_e64 s[16:17], 48, v219
	v_mfma_f32_32x32x16_bf16 v[30:45], v[202:205], v[230:233], v[30:45]
	ds_read_b128 v[202:205], v218 offset:4640
	v_cndmask_b32_e64 v101, v220, v101, s[52:53]
	v_cmp_le_i32_e64 s[52:53], 17, v219
	v_cndmask_b32_e64 v86, v220, v86, s[14:15]
	v_cmp_le_i32_e64 s[14:15], 49, v219
	v_cndmask_b32_e64 v102, v220, v102, s[16:17]
	v_cmp_le_i32_e64 s[16:17], 18, v219
	v_cndmask_b32_e64 v87, v220, v87, s[52:53]
	v_cmp_le_i32_e64 s[52:53], 50, v219
	v_cndmask_b32_e64 v103, v220, v103, s[14:15]
	v_cmp_le_i32_e64 s[14:15], 19, v219
	v_cndmask_b32_e64 v88, v220, v88, s[16:17]
	v_mfma_f32_32x32x16_bf16 v[14:29], v[206:209], v[234:237], v[14:29]
	ds_read_b128 v[206:209], v218 offset:64
	v_cmp_le_i32_e64 s[16:17], 51, v219
	v_cndmask_b32_e64 v104, v220, v104, s[52:53]
	v_cmp_le_i32_e64 s[52:53], 24, v219
	v_cndmask_b32_e64 v89, v220, v89, s[14:15]
	v_cmp_le_i32_e64 s[14:15], 56, v219
	v_cndmask_b32_e64 v105, v220, v105, s[16:17]
	v_cmp_le_i32_e64 s[16:17], 25, v219
	v_cndmask_b32_e64 v90, v220, v90, s[52:53]
	v_cmp_le_i32_e64 s[52:53], 57, v219
	v_cndmask_b32_e64 v106, v220, v106, s[14:15]
	v_mfma_f32_32x32x16_bf16 v[30:45], v[210:213], v[234:237], v[30:45]
	ds_read_b128 v[210:213], v218 offset:4672
	v_cmp_le_i32_e64 s[14:15], 26, v219
	v_cndmask_b32_e64 v91, v220, v91, s[16:17]
	v_cmp_le_i32_e64 s[16:17], 58, v219
	v_cndmask_b32_e64 v107, v220, v107, s[52:53]
	v_cmp_le_i32_e64 s[52:53], 27, v219
	v_cndmask_b32_e64 v92, v220, v92, s[14:15]
	v_cmp_le_i32_e64 s[14:15], 59, v219
	v_cndmask_b32_e64 v108, v220, v108, s[16:17]
	v_cndmask_b32_e64 v93, v220, v93, s[52:53]
	v_cndmask_b32_e64 v109, v220, v109, s[14:15]
	v_mfma_f32_32x32x16_bf16 v[14:29], v[214:217], v[238:241], v[14:29]
	ds_read_b128 v[214:217], v218 offset:96
	v_max3_f32 v124, v78, v79, v80
	v_max3_f32 v125, v81, v82, v83
	v_max3_f32 v124, v124, v84, v85
	v_max3_f32 v125, v125, v86, v87
	v_max3_f32 v124, v124, v88, v89
	v_max3_f32 v125, v125, v90, v91
	v_max3_f32 v124, v124, v92, v93
	v_max3_f32 v125, v125, v94, v95
	v_max3_f32 v124, v124, v96, v97
	v_max3_f32 v125, v125, v98, v99
	v_mfma_f32_32x32x16_bf16 v[30:45], v[222:225], v[238:241], v[30:45]
	s_waitcnt lgkmcnt(14)
	ds_read_b128 v[222:225], v218 offset:4704
	v_max3_f32 v124, v124, v100, v101
	v_max3_f32 v125, v125, v102, v103
	v_max3_f32 v124, v124, v104, v105
	v_max3_f32 v125, v125, v106, v107
	v_max3_f32 v124, v124, v108, v109
	v_max_f32_e32 v124, v124, v125
	v_mov_b32_e32 v125, v124
	s_nop 1
	v_permlane32_swap_b32_e32 v124, v125
	v_max_f32_e32 v126, v124, v125
	v_lshl_add_u64 v[242:243], v[242:243], 0, s[46:47]
	v_lshl_add_u64 v[246:247], v[246:247], 0, s[46:47]
	s_branch .Lf3_tail5

.Lf3_resc_rett4CONLY:
	s_waitcnt lgkmcnt(0)
	ds_read_b64_tr_b16 v[190:191], v159 offset:26624
	ds_read_b64_tr_b16 v[192:193], v159 offset:27136
	ds_read_b64_tr_b16 v[194:195], v159 offset:30720
	ds_read_b64_tr_b16 v[196:197], v159 offset:31232
	ds_read_b64_tr_b16 v[198:199], v159 offset:27648
	ds_read_b64_tr_b16 v[200:201], v159 offset:28160
	ds_read_b64_tr_b16 v[202:203], v159 offset:31744
	ds_read_b64_tr_b16 v[204:205], v159 offset:32256
	ds_read_b64_tr_b16 v[206:207], v159 offset:28672
	ds_read_b64_tr_b16 v[208:209], v159 offset:29184
	ds_read_b64_tr_b16 v[210:211], v159 offset:32768
	ds_read_b64_tr_b16 v[212:213], v159 offset:33280
	ds_read_b64_tr_b16 v[214:215], v159 offset:29696
	ds_read_b64_tr_b16 v[216:217], v159 offset:30208
	v_sub_f32_e32 v46, v46, v160
	v_sub_f32_e32 v47, v47, v160
	v_sub_f32_e32 v48, v48, v160
	v_sub_f32_e32 v49, v49, v160
	v_sub_f32_e32 v50, v50, v160
	v_sub_f32_e32 v51, v51, v160
	v_sub_f32_e32 v52, v52, v160
	v_sub_f32_e32 v53, v53, v160
	v_exp_f32_e32 v46, v46
	v_exp_f32_e32 v47, v47
	v_exp_f32_e32 v48, v48
	v_exp_f32_e32 v49, v49
	v_exp_f32_e32 v50, v50
	v_exp_f32_e32 v51, v51
	v_exp_f32_e32 v52, v52
	v_exp_f32_e32 v53, v53
	v_add_f32_e32 v122, v46, v47
	v_add_f32_e32 v123, v48, v49
	v_add_f32_e32 v122, v122, v50
	v_add_f32_e32 v123, v123, v51
	v_add_f32_e32 v122, v122, v52
	v_add_f32_e32 v123, v123, v53
	v_cvt_pk_bf16_f32 v226, v46, v47
	v_cvt_pk_bf16_f32 v227, v48, v49
	v_cvt_pk_bf16_f32 v228, v50, v51
	v_cvt_pk_bf16_f32 v229, v52, v53
	v_sub_f32_e32 v54, v54, v160
	v_sub_f32_e32 v55, v55, v160
	v_sub_f32_e32 v56, v56, v160
	v_sub_f32_e32 v57, v57, v160
	v_sub_f32_e32 v58, v58, v160
	v_sub_f32_e32 v59, v59, v160
	v_sub_f32_e32 v60, v60, v160
	v_sub_f32_e32 v61, v61, v160
	v_exp_f32_e32 v54, v54
	v_exp_f32_e32 v55, v55
	v_exp_f32_e32 v56, v56
	v_exp_f32_e32 v57, v57
	v_exp_f32_e32 v58, v58
	v_exp_f32_e32 v59, v59
	v_exp_f32_e32 v60, v60
	v_exp_f32_e32 v61, v61
	v_add_f32_e32 v122, v122, v54
	v_add_f32_e32 v123, v123, v55
	v_add_f32_e32 v122, v122, v56
	v_add_f32_e32 v123, v123, v57
	v_add_f32_e32 v122, v122, v58
	v_add_f32_e32 v123, v123, v59
	v_add_f32_e32 v122, v122, v60
	v_add_f32_e32 v123, v123, v61
	v_cvt_pk_bf16_f32 v230, v54, v55
	v_cvt_pk_bf16_f32 v231, v56, v57
	v_cvt_pk_bf16_f32 v232, v58, v59
	v_cvt_pk_bf16_f32 v233, v60, v61
	v_sub_f32_e32 v62, v62, v160
	v_sub_f32_e32 v63, v63, v160
	v_sub_f32_e32 v64, v64, v160
	v_sub_f32_e32 v65, v65, v160
	v_sub_f32_e32 v66, v66, v160
	v_sub_f32_e32 v67, v67, v160
	v_sub_f32_e32 v68, v68, v160
	v_sub_f32_e32 v69, v69, v160
	v_exp_f32_e32 v62, v62
	v_exp_f32_e32 v63, v63
	v_exp_f32_e32 v64, v64
	v_exp_f32_e32 v65, v65
	v_exp_f32_e32 v66, v66
	v_exp_f32_e32 v67, v67
	v_exp_f32_e32 v68, v68
	v_exp_f32_e32 v69, v69
	v_add_f32_e32 v122, v122, v62
	v_add_f32_e32 v123, v123, v63
	v_add_f32_e32 v122, v122, v64
	v_add_f32_e32 v123, v123, v65
	v_add_f32_e32 v122, v122, v66
	v_add_f32_e32 v123, v123, v67
	v_add_f32_e32 v122, v122, v68
	v_add_f32_e32 v123, v123, v69
	v_cvt_pk_bf16_f32 v234, v62, v63
	v_cvt_pk_bf16_f32 v235, v64, v65
	v_cvt_pk_bf16_f32 v236, v66, v67
	v_cvt_pk_bf16_f32 v237, v68, v69
	v_sub_f32_e32 v70, v70, v160
	v_sub_f32_e32 v71, v71, v160
	v_sub_f32_e32 v72, v72, v160
	v_sub_f32_e32 v73, v73, v160
	v_sub_f32_e32 v74, v74, v160
	v_sub_f32_e32 v75, v75, v160
	v_sub_f32_e32 v76, v76, v160
	v_sub_f32_e32 v77, v77, v160
	v_exp_f32_e32 v70, v70
	v_exp_f32_e32 v71, v71
	v_exp_f32_e32 v72, v72
	v_exp_f32_e32 v73, v73
	v_exp_f32_e32 v74, v74
	v_exp_f32_e32 v75, v75
	v_exp_f32_e32 v76, v76
	v_exp_f32_e32 v77, v77
	v_add_f32_e32 v122, v122, v70
	v_add_f32_e32 v123, v123, v71
	v_add_f32_e32 v122, v122, v72
	v_add_f32_e32 v123, v123, v73
	v_add_f32_e32 v122, v122, v74
	v_add_f32_e32 v123, v123, v75
	v_add_f32_e32 v122, v122, v76
	v_add_f32_e32 v123, v123, v77
	v_cvt_pk_bf16_f32 v238, v70, v71
	v_cvt_pk_bf16_f32 v239, v72, v73
	v_cvt_pk_bf16_f32 v240, v74, v75
	v_cvt_pk_bf16_f32 v241, v76, v77
	v_add_f32_e32 v122, v122, v123
	v_add_f32_e32 v161, v161, v122
	s_waitcnt lgkmcnt(8)
	ds_read_b64_tr_b16 v[222:223], v159 offset:33792
	ds_read_b64_tr_b16 v[224:225], v159 offset:34304
	s_waitcnt vmcnt(0)
	ds_write_b128 v155, v[118:121] offset:34816
	s_waitcnt lgkmcnt(0)
	s_barrier
	v_mfma_f32_32x32x16_bf16 v[14:29], v[190:193], v[226:229], v[14:29]
	v_mfma_f32_32x32x16_bf16 v[30:45], v[194:197], v[226:229], v[30:45]
	v_mfma_f32_32x32x16_bf16 v[14:29], v[198:201], v[230:233], v[14:29]
	v_mfma_f32_32x32x16_bf16 v[30:45], v[202:205], v[230:233], v[30:45]
	v_mfma_f32_32x32x16_bf16 v[14:29], v[206:209], v[234:237], v[14:29]
	v_mfma_f32_32x32x16_bf16 v[30:45], v[210:213], v[234:237], v[30:45]
	v_mfma_f32_32x32x16_bf16 v[14:29], v[214:217], v[238:241], v[14:29]
	v_mfma_f32_32x32x16_bf16 v[30:45], v[222:225], v[238:241], v[30:45]
	v_lshl_add_u64 v[242:243], v[242:243], 0, s[46:47]
	v_lshl_add_u64 v[246:247], v[246:247], 0, s[46:47]
.Lf3_tail5:
	s_cmp_eq_u32 s11, 3
	s_cbranch_scc1 .Lf3_t5_CONLY
	s_waitcnt lgkmcnt(0)
	s_waitcnt lgkmcnt(0)
	s_barrier
	v_lshl_add_u64 v[244:245], v[244:245], 0, s[46:47]
	v_lshl_add_u64 v[248:249], v[248:249], 0, s[46:47]
	v_lshl_add_u64 v[250:251], v[250:251], 0, s[48:49]
	s_branch .Lf3_done

.Lf3_resc_rett5CONLY:
	s_waitcnt lgkmcnt(0)
	ds_read_b64_tr_b16 v[190:191], v159 offset:34816
	ds_read_b64_tr_b16 v[192:193], v159 offset:35328
	ds_read_b64_tr_b16 v[194:195], v159 offset:38912
	ds_read_b64_tr_b16 v[196:197], v159 offset:39424
	ds_read_b64_tr_b16 v[198:199], v159 offset:35840
	ds_read_b64_tr_b16 v[200:201], v159 offset:36352
	ds_read_b64_tr_b16 v[202:203], v159 offset:39936
	ds_read_b64_tr_b16 v[204:205], v159 offset:40448
	ds_read_b64_tr_b16 v[206:207], v159 offset:36864
	ds_read_b64_tr_b16 v[208:209], v159 offset:37376
	ds_read_b64_tr_b16 v[210:211], v159 offset:40960
	ds_read_b64_tr_b16 v[212:213], v159 offset:41472
	ds_read_b64_tr_b16 v[214:215], v159 offset:37888
	ds_read_b64_tr_b16 v[216:217], v159 offset:38400
	v_sub_f32_e32 v78, v78, v160
	v_sub_f32_e32 v79, v79, v160
	v_sub_f32_e32 v80, v80, v160
	v_sub_f32_e32 v81, v81, v160
	v_sub_f32_e32 v82, v82, v160
	v_sub_f32_e32 v83, v83, v160
	v_sub_f32_e32 v84, v84, v160
	v_sub_f32_e32 v85, v85, v160
	v_exp_f32_e32 v78, v78
	v_exp_f32_e32 v79, v79
	v_exp_f32_e32 v80, v80
	v_exp_f32_e32 v81, v81
	v_exp_f32_e32 v82, v82
	v_exp_f32_e32 v83, v83
	v_exp_f32_e32 v84, v84
	v_exp_f32_e32 v85, v85
	v_add_f32_e32 v122, v78, v79
	v_add_f32_e32 v123, v80, v81
	v_add_f32_e32 v122, v122, v82
	v_add_f32_e32 v123, v123, v83
	v_add_f32_e32 v122, v122, v84
	v_add_f32_e32 v123, v123, v85
	v_cvt_pk_bf16_f32 v226, v78, v79
	v_cvt_pk_bf16_f32 v227, v80, v81
	v_cvt_pk_bf16_f32 v228, v82, v83
	v_cvt_pk_bf16_f32 v229, v84, v85
	v_sub_f32_e32 v86, v86, v160
	v_sub_f32_e32 v87, v87, v160
	v_sub_f32_e32 v88, v88, v160
	v_sub_f32_e32 v89, v89, v160
	v_sub_f32_e32 v90, v90, v160
	v_sub_f32_e32 v91, v91, v160
	v_sub_f32_e32 v92, v92, v160
	v_sub_f32_e32 v93, v93, v160
	v_exp_f32_e32 v86, v86
	v_exp_f32_e32 v87, v87
	v_exp_f32_e32 v88, v88
	v_exp_f32_e32 v89, v89
	v_exp_f32_e32 v90, v90
	v_exp_f32_e32 v91, v91
	v_exp_f32_e32 v92, v92
	v_exp_f32_e32 v93, v93
	v_add_f32_e32 v122, v122, v86
	v_add_f32_e32 v123, v123, v87
	v_add_f32_e32 v122, v122, v88
	v_add_f32_e32 v123, v123, v89
	v_add_f32_e32 v122, v122, v90
	v_add_f32_e32 v123, v123, v91
	v_add_f32_e32 v122, v122, v92
	v_add_f32_e32 v123, v123, v93
	v_cvt_pk_bf16_f32 v230, v86, v87
	v_cvt_pk_bf16_f32 v231, v88, v89
	v_cvt_pk_bf16_f32 v232, v90, v91
	v_cvt_pk_bf16_f32 v233, v92, v93
	v_sub_f32_e32 v94, v94, v160
	v_sub_f32_e32 v95, v95, v160
	v_sub_f32_e32 v96, v96, v160
	v_sub_f32_e32 v97, v97, v160
	v_sub_f32_e32 v98, v98, v160
	v_sub_f32_e32 v99, v99, v160
	v_sub_f32_e32 v100, v100, v160
	v_sub_f32_e32 v101, v101, v160
	v_exp_f32_e32 v94, v94
	v_exp_f32_e32 v95, v95
	v_exp_f32_e32 v96, v96
	v_exp_f32_e32 v97, v97
	v_exp_f32_e32 v98, v98
	v_exp_f32_e32 v99, v99
	v_exp_f32_e32 v100, v100
	v_exp_f32_e32 v101, v101
	v_add_f32_e32 v122, v122, v94
	v_add_f32_e32 v123, v123, v95
	v_add_f32_e32 v122, v122, v96
	v_add_f32_e32 v123, v123, v97
	v_add_f32_e32 v122, v122, v98
	v_add_f32_e32 v123, v123, v99
	v_add_f32_e32 v122, v122, v100
	v_add_f32_e32 v123, v123, v101
	v_cvt_pk_bf16_f32 v234, v94, v95
	v_cvt_pk_bf16_f32 v235, v96, v97
	v_cvt_pk_bf16_f32 v236, v98, v99
	v_cvt_pk_bf16_f32 v237, v100, v101
	v_sub_f32_e32 v102, v102, v160
	v_sub_f32_e32 v103, v103, v160
	v_sub_f32_e32 v104, v104, v160
	v_sub_f32_e32 v105, v105, v160
	v_sub_f32_e32 v106, v106, v160
	v_sub_f32_e32 v107, v107, v160
	v_sub_f32_e32 v108, v108, v160
	v_sub_f32_e32 v109, v109, v160
	v_exp_f32_e32 v102, v102
	v_exp_f32_e32 v103, v103
	v_exp_f32_e32 v104, v104
	v_exp_f32_e32 v105, v105
	v_exp_f32_e32 v106, v106
	v_exp_f32_e32 v107, v107
	v_exp_f32_e32 v108, v108
	v_exp_f32_e32 v109, v109
	v_add_f32_e32 v122, v122, v102
	v_add_f32_e32 v123, v123, v103
	v_add_f32_e32 v122, v122, v104
	v_add_f32_e32 v123, v123, v105
	v_add_f32_e32 v122, v122, v106
	v_add_f32_e32 v123, v123, v107
	v_add_f32_e32 v122, v122, v108
	v_add_f32_e32 v123, v123, v109
	v_cvt_pk_bf16_f32 v238, v102, v103
	v_cvt_pk_bf16_f32 v239, v104, v105
	v_cvt_pk_bf16_f32 v240, v106, v107
	v_cvt_pk_bf16_f32 v241, v108, v109
	v_add_f32_e32 v122, v122, v123
	v_add_f32_e32 v161, v161, v122
	s_waitcnt lgkmcnt(8)
	ds_read_b64_tr_b16 v[222:223], v159 offset:41984
	ds_read_b64_tr_b16 v[224:225], v159 offset:42496
	s_waitcnt lgkmcnt(0)
	s_barrier
	v_mfma_f32_32x32x16_bf16 v[14:29], v[190:193], v[226:229], v[14:29]
	v_mfma_f32_32x32x16_bf16 v[30:45], v[194:197], v[226:229], v[30:45]
	v_mfma_f32_32x32x16_bf16 v[14:29], v[198:201], v[230:233], v[14:29]
	v_mfma_f32_32x32x16_bf16 v[30:45], v[202:205], v[230:233], v[30:45]
	v_mfma_f32_32x32x16_bf16 v[14:29], v[206:209], v[234:237], v[14:29]
	v_mfma_f32_32x32x16_bf16 v[30:45], v[210:213], v[234:237], v[30:45]
	v_mfma_f32_32x32x16_bf16 v[14:29], v[214:217], v[238:241], v[14:29]
	v_mfma_f32_32x32x16_bf16 v[30:45], v[222:225], v[238:241], v[30:45]
	v_lshl_add_u64 v[244:245], v[244:245], 0, s[46:47]
	v_lshl_add_u64 v[248:249], v[248:249], 0, s[46:47]
	v_lshl_add_u64 v[250:251], v[250:251], 0, s[48:49]
.Lf3_done:
	s_waitcnt vmcnt(0) lgkmcnt(0)
	s_branch .LBB0_712
.Lf3_resca:
	s_nop 15
	v_max_f32_e32 v127, v160, v126
	v_sub_f32_e32 v128, v160, v127
	v_exp_f32_e32 v128, v128
	v_mov_b32_e32 v160, v127
	v_mul_f32_e32 v161, v161, v128
	v_mul_f32_e32 v14, v14, v128
	v_mul_f32_e32 v15, v15, v128
	v_mul_f32_e32 v16, v16, v128
	v_mul_f32_e32 v17, v17, v128
	v_mul_f32_e32 v18, v18, v128
	v_mul_f32_e32 v19, v19, v128
	v_mul_f32_e32 v20, v20, v128
	v_mul_f32_e32 v21, v21, v128
	v_mul_f32_e32 v22, v22, v128
	v_mul_f32_e32 v23, v23, v128
	v_mul_f32_e32 v24, v24, v128
	v_mul_f32_e32 v25, v25, v128
	v_mul_f32_e32 v26, v26, v128
	v_mul_f32_e32 v27, v27, v128
	v_mul_f32_e32 v28, v28, v128
	v_mul_f32_e32 v29, v29, v128
	v_mul_f32_e32 v30, v30, v128
	v_mul_f32_e32 v31, v31, v128
	v_mul_f32_e32 v32, v32, v128
	v_mul_f32_e32 v33, v33, v128
	v_mul_f32_e32 v34, v34, v128
	v_mul_f32_e32 v35, v35, v128
	v_mul_f32_e32 v36, v36, v128
	v_mul_f32_e32 v37, v37, v128
	v_mul_f32_e32 v38, v38, v128
	v_mul_f32_e32 v39, v39, v128
	v_mul_f32_e32 v40, v40, v128
	v_mul_f32_e32 v41, v41, v128
	v_mul_f32_e32 v42, v42, v128
	v_mul_f32_e32 v43, v43, v128
	v_mul_f32_e32 v44, v44, v128
	v_mul_f32_e32 v45, v45, v128
	s_branch .Lf3_resc_reta

.Lf3_resct5CONLY:
	s_nop 15
	v_max_f32_e32 v127, v160, v126
	v_sub_f32_e32 v128, v160, v127
	v_exp_f32_e32 v128, v128
	v_mov_b32_e32 v160, v127
	v_mul_f32_e32 v161, v161, v128
	v_mul_f32_e32 v14, v14, v128
	v_mul_f32_e32 v15, v15, v128
	v_mul_f32_e32 v16, v16, v128
	v_mul_f32_e32 v17, v17, v128
	v_mul_f32_e32 v18, v18, v128
	v_mul_f32_e32 v19, v19, v128
	v_mul_f32_e32 v20, v20, v128
	v_mul_f32_e32 v21, v21, v128
	v_mul_f32_e32 v22, v22, v128
	v_mul_f32_e32 v23, v23, v128
	v_mul_f32_e32 v24, v24, v128
	v_mul_f32_e32 v25, v25, v128
	v_mul_f32_e32 v26, v26, v128
	v_mul_f32_e32 v27, v27, v128
	v_mul_f32_e32 v28, v28, v128
	v_mul_f32_e32 v29, v29, v128
	v_mul_f32_e32 v30, v30, v128
	v_mul_f32_e32 v31, v31, v128
	v_mul_f32_e32 v32, v32, v128
	v_mul_f32_e32 v33, v33, v128
	v_mul_f32_e32 v34, v34, v128
	v_mul_f32_e32 v35, v35, v128
	v_mul_f32_e32 v36, v36, v128
	v_mul_f32_e32 v37, v37, v128
	v_mul_f32_e32 v38, v38, v128
	v_mul_f32_e32 v39, v39, v128
	v_mul_f32_e32 v40, v40, v128
	v_mul_f32_e32 v41, v41, v128
	v_mul_f32_e32 v42, v42, v128
	v_mul_f32_e32 v43, v43, v128
	v_mul_f32_e32 v44, v44, v128
	v_mul_f32_e32 v45, v45, v128
	s_branch .Lf3_resc_rett5CONLY
.LBB0_712:
	v_mov_b32_e32 v0, v161
	s_nop 1
	v_permlane32_swap_b32_e32 v161, v0
	v_add_f32_e32 v0, v161, v0
	v_rcp_f32_e32 v2, v0
	v_or3_b32 v134, v156, s56, v134
	s_mov_b64 s[4:5], 0
